# K-loops of the four GEMM phases: one static s_setprio 1 for the younger wave half (waves 4-7) before the loop, all per-segment s_setprio flips deleted; W_out phase ds_read base hoist moved to the real
# speedup vs baseline: 1.0210x; 1.0076x over previous
; #define PG8_STAGE(bufoff, gbase, voff) do { _Pragma("unroll") for (int _i = 0; _i < 2; ++_i) \
;         __builtin_amdgcn_global_load_lds((const unsigned*)((const char*)(gbase) + (voff)[_i]), (PG8_LAS unsigned*)(lds + (bufoff) + ldsw + _i * 8192), 16, 0, 0); } while (0)
; #define PG8_LDA(dst, b, h) do { _Pragma("unroll") for (int m = 0; m < 4; ++m) _Pragma("unroll") for (int k = 0; k < 2; ++k) dst[m][k] = *(const PG8_LAS bf16x8*)(lds + PG8_SA(b, h) + aoff + m * 2048 + k * 1024); } while (0)
; #define PG8_LDB(dst, b, h) do { _Pragma("unroll") for (int n = 0; n < 2; ++n) _Pragma("unroll") for (int k = 0; k < 2; ++k) dst[n][k] = *(const PG8_LAS bf16x8*)(lds + PG8_SB(b, h) + boff + n * 2048 + k * 1024); } while (0)
; #define PG8_MMA(ai, bj, At, Bt) do { __builtin_amdgcn_s_setprio(1); _Pragma("unroll") for (int m = 0; m < 4; ++m) _Pragma("unroll") for (int n = 0; n < 2; ++n) _Pragma("unroll") for (int k = 0; k < 2; ++k) \
;         acc[ai][bj][m][n] = __builtin_amdgcn_mfma_f32_16x16x32_bf16(Bt[n][k], At[m][k], acc[ai][bj][m][n], 0, 0, 0); __builtin_amdgcn_s_setprio(0); } while (0)
; #define PG8_WAIT_V(n) asm volatile("s_waitcnt vmcnt(" #n ")" ::: "memory")
; #define PG8_WAIT_L(n) asm volatile("s_waitcnt lgkmcnt(" #n ")" ::: "memory")
; #define PG8_BAR __builtin_amdgcn_s_barrier()
; #define PG8_SCHED __builtin_amdgcn_sched_barrier(0)
; template <class Epi, class Sched, bool ALIGN_EPI = false, bool SP2 = false>
; __device__ __forceinline__ void gemm_phase(PG8_LAS unsigned char* lds, const Gemm g, const Sched& S, const Epi& E) {
;     ...
;             PG8_LDB(B0, 0, 0); PG8_LDB(B1, 0, 1); PG8_SCHED; PG8_LDA(At, 0, 0); PG8_STAGE(PG8_SA(1, 1), a1 + hstep, voffA);
;             PG8_WAIT_V(8); PG8_WAIT_L(0); PG8_BAR; PG8_MMA(0, 0, At, B0); PG8_MMA(0, 1, At, B1); PG8_BAR; PG8_SCHED;
;     ...
; #pragma unroll
;         for (int a = 0; a < 2; ++a)
; #pragma unroll
;             for (int b = 0; b < 2; ++b)
; #pragma unroll
;                 for (int m = 0; m < 4; ++m)
; #pragma unroll
;                     for (int n = 0; n < 2; ++n) acc[a][b][m][n] = (f32x4){0.f, 0.f, 0.f, 0.f};
;         cur = nxt; cA = nA; cB = nB; ++ui;
.LBB0_173:
	s_add_i32 s51, s51, 1
	s_mov_b64 s[2:3], s[6:7]
	s_mov_b32 s53, s14
	s_lshl_b32 s6, s51, 3
	v_readlane_b32 s14, v248, 25
	s_add_i32 s14, s6, s14
	v_readlane_b32 s15, v248, 26
	s_cmp_lt_i32 s14, 14
	s_cselect_b64 s[38:39], -1, 0
	s_ashr_i32 s15, s14, 31
	s_lshl_b64 s[6:7], s[14:15], 20
	s_add_u32 s6, s44, s6
	s_addc_u32 s7, s45, s7
	s_and_b64 s[36:37], s[38:39], exec
	v_mov_b32_e32 v4, 0
	s_cselect_b32 s15, s7, s3
	s_cselect_b32 s52, s6, s2
	s_mov_b32 s54, -2
	s_mov_b64 s[2:3], 0
	v_mov_b32_e32 v5, v4
	v_mov_b32_e32 v6, v4
	v_mov_b32_e32 v7, v4
	v_mov_b32_e32 v8, v4
	v_mov_b32_e32 v9, v4
	v_mov_b32_e32 v10, v4
	v_mov_b32_e32 v11, v4
	v_mov_b32_e32 v20, v4
	v_mov_b32_e32 v21, v4
	v_mov_b32_e32 v22, v4
	v_mov_b32_e32 v23, v4
	v_mov_b32_e32 v24, v4
	v_mov_b32_e32 v25, v4
	v_mov_b32_e32 v26, v4
	v_mov_b32_e32 v27, v4
	v_mov_b32_e32 v36, v4
	v_mov_b32_e32 v37, v4
	v_mov_b32_e32 v38, v4
	v_mov_b32_e32 v39, v4
	v_mov_b32_e32 v40, v4
	v_mov_b32_e32 v41, v4
	v_mov_b32_e32 v42, v4
	v_mov_b32_e32 v43, v4
	v_mov_b32_e32 v52, v4
	v_mov_b32_e32 v53, v4
	v_mov_b32_e32 v54, v4
	v_mov_b32_e32 v55, v4
	v_mov_b32_e32 v56, v4
	v_mov_b32_e32 v57, v4
	v_mov_b32_e32 v58, v4
	v_mov_b32_e32 v59, v4
	v_mov_b32_e32 v12, v4
	v_mov_b32_e32 v13, v4
	v_mov_b32_e32 v14, v4
	v_mov_b32_e32 v15, v4
	v_mov_b32_e32 v16, v4
	v_mov_b32_e32 v17, v4
	v_mov_b32_e32 v18, v4
	v_mov_b32_e32 v19, v4
	v_mov_b32_e32 v28, v4
	v_mov_b32_e32 v29, v4
	v_mov_b32_e32 v30, v4
	v_mov_b32_e32 v31, v4
	v_mov_b32_e32 v32, v4
	v_mov_b32_e32 v33, v4
	v_mov_b32_e32 v34, v4
	v_mov_b32_e32 v35, v4
	v_mov_b32_e32 v44, v4
	v_mov_b32_e32 v45, v4
	v_mov_b32_e32 v46, v4
	v_mov_b32_e32 v47, v4
	v_mov_b32_e32 v48, v4
	v_mov_b32_e32 v49, v4
	v_mov_b32_e32 v50, v4
	v_mov_b32_e32 v51, v4
	v_mov_b32_e32 v60, v4
	v_mov_b32_e32 v61, v4
	v_mov_b32_e32 v62, v4
	v_mov_b32_e32 v63, v4
	v_mov_b32_e32 v64, v4
	v_mov_b32_e32 v65, v4
	v_mov_b32_e32 v66, v4
	v_mov_b32_e32 v67, v4
	v_mov_b32_e32 v68, v4
	v_mov_b32_e32 v69, v4
	v_mov_b32_e32 v70, v4
	v_mov_b32_e32 v71, v4
	v_mov_b32_e32 v72, v4
	v_mov_b32_e32 v73, v4
	v_mov_b32_e32 v74, v4
	v_mov_b32_e32 v75, v4
	v_mov_b32_e32 v84, v4
	v_mov_b32_e32 v85, v4
	v_mov_b32_e32 v86, v4
	v_mov_b32_e32 v87, v4
	v_mov_b32_e32 v88, v4
	v_mov_b32_e32 v89, v4
	v_mov_b32_e32 v90, v4
	v_mov_b32_e32 v91, v4
	v_mov_b32_e32 v100, v4
	v_mov_b32_e32 v101, v4
	v_mov_b32_e32 v102, v4
	v_mov_b32_e32 v103, v4
	v_mov_b32_e32 v104, v4
	v_mov_b32_e32 v105, v4
	v_mov_b32_e32 v106, v4
	v_mov_b32_e32 v107, v4
	v_mov_b32_e32 v116, v4
	v_mov_b32_e32 v117, v4
	v_mov_b32_e32 v118, v4
	v_mov_b32_e32 v119, v4
	v_mov_b32_e32 v120, v4
	v_mov_b32_e32 v121, v4
	v_mov_b32_e32 v122, v4
	v_mov_b32_e32 v123, v4
	v_mov_b32_e32 v76, v4
	v_mov_b32_e32 v77, v4
	v_mov_b32_e32 v78, v4
	v_mov_b32_e32 v79, v4
	v_mov_b32_e32 v80, v4
	v_mov_b32_e32 v81, v4
	v_mov_b32_e32 v82, v4
	v_mov_b32_e32 v83, v4
	v_mov_b32_e32 v92, v4
	v_mov_b32_e32 v93, v4
	v_mov_b32_e32 v94, v4
	v_mov_b32_e32 v95, v4
	v_mov_b32_e32 v96, v4
	v_mov_b32_e32 v97, v4
	v_mov_b32_e32 v98, v4
	v_mov_b32_e32 v99, v4
	v_mov_b32_e32 v108, v4
	v_mov_b32_e32 v109, v4
	v_mov_b32_e32 v110, v4
	v_mov_b32_e32 v111, v4
	v_mov_b32_e32 v112, v4
	v_mov_b32_e32 v113, v4
	v_mov_b32_e32 v114, v4
	v_mov_b32_e32 v115, v4
	v_mov_b32_e32 v124, v4
	v_mov_b32_e32 v125, v4
	v_mov_b32_e32 v126, v4
	v_mov_b32_e32 v127, v4
	v_mov_b32_e32 v128, v4
	v_mov_b32_e32 v129, v4
	v_mov_b32_e32 v130, v4
	v_mov_b32_e32 v131, v4
	v_add_u32_e32 v168, 0x10000, v3
	v_add_u32_e32 v169, 0x14000, v3
	v_add_u32_e32 v170, 0x18000, v3
	v_add_u32_e32 v171, 0x1c000, v3
	s_cmp_lg_u64 s[10:11], 0
	s_cbranch_scc1 .Lprio_P1
	s_setprio 1
.Lprio_P1:
.LBB0_174:
	s_add_u32 s36, s31, s2
	s_addc_u32 s37, s91, s3
	s_add_u32 s36, s36, 0x16200100
	s_addc_u32 s37, s37, 0
	s_add_u32 s55, s12, s2
	s_addc_u32 s56, s13, s3
	s_add_i32 s57, 0, 0x10000
	s_cmpk_eq_i32 s2, 0xf00
	s_cselect_b32 s41, s1, s37
	s_cselect_b32 s40, s0, s36
	s_cselect_b32 s37, s15, s56
	s_cselect_b32 s36, s52, s55
	s_add_i32 s55, 0, 0x14000
	ds_read_b128 v[142:145], v168
	ds_read_b128 v[146:149], v168 offset:1024
	ds_read_b128 v[156:159], v168 offset:2048
	ds_read_b128 v[172:175], v168 offset:3072
	ds_read_b128 v[176:179], v169
	ds_read_b128 v[180:183], v169 offset:1024
	ds_read_b128 v[184:187], v169 offset:2048
	ds_read_b128 v[188:191], v169 offset:3072
	v_lshl_add_u64 v[150:151], v[138:139], 0, s[2:3]
	s_add_i32 m0, s43, 0xc000
	ds_read_b128 v[192:195], v154
	ds_read_b128 v[196:199], v154 offset:1024
	ds_read_b128 v[200:203], v154 offset:2048
	ds_read_b128 v[212:215], v154 offset:3072
	ds_read_b128 v[216:219], v154 offset:4096
	ds_read_b128 v[220:223], v154 offset:5120
	ds_read_b128 v[224:227], v154 offset:6144
	ds_read_b128 v[228:231], v154 offset:7168
	global_load_lds_dwordx4 v[150:151], off
	v_lshl_add_u64 v[150:151], v[140:141], 0, s[2:3]
	s_add_i32 m0, s43, 0xe000
	s_nop 0
	global_load_lds_dwordx4 v[150:151], off
	s_waitcnt vmcnt(8)
	s_waitcnt lgkmcnt(0)
	s_barrier
; #define PG8_STAGE(bufoff, gbase, voff) do { _Pragma("unroll") for (int _i = 0; _i < 2; ++_i) \
;         __builtin_amdgcn_global_load_lds((const unsigned*)((const char*)(gbase) + (voff)[_i]), (PG8_LAS unsigned*)(lds + (bufoff) + ldsw + _i * 8192), 16, 0, 0); } while (0)
; #define PG8_LDA(dst, b, h) do { _Pragma("unroll") for (int m = 0; m < 4; ++m) _Pragma("unroll") for (int k = 0; k < 2; ++k) dst[m][k] = *(const PG8_LAS bf16x8*)(lds + PG8_SA(b, h) + aoff + m * 2048 + k * 1024); } while (0)
; #define PG8_LDB(dst, b, h) do { _Pragma("unroll") for (int n = 0; n < 2; ++n) _Pragma("unroll") for (int k = 0; k < 2; ++k) dst[n][k] = *(const PG8_LAS bf16x8*)(lds + PG8_SB(b, h) + boff + n * 2048 + k * 1024); } while (0)
; #define PG8_MMA(ai, bj, At, Bt) do { __builtin_amdgcn_s_setprio(1); _Pragma("unroll") for (int m = 0; m < 4; ++m) _Pragma("unroll") for (int n = 0; n < 2; ++n) _Pragma("unroll") for (int k = 0; k < 2; ++k) \
;         acc[ai][bj][m][n] = __builtin_amdgcn_mfma_f32_16x16x32_bf16(Bt[n][k], At[m][k], acc[ai][bj][m][n], 0, 0, 0); __builtin_amdgcn_s_setprio(0); } while (0)
; #define PG8_WAIT_V(n) asm volatile("s_waitcnt vmcnt(" #n ")" ::: "memory")
; #define PG8_WAIT_L(n) asm volatile("s_waitcnt lgkmcnt(" #n ")" ::: "memory")
; #define PG8_BAR __builtin_amdgcn_s_barrier()
; #define PG8_SCHED __builtin_amdgcn_sched_barrier(0)
; template <class Epi, class Sched, bool ALIGN_EPI = false, bool SP2 = false>
; __device__ __forceinline__ void gemm_phase(PG8_LAS unsigned char* lds, const Gemm g, const Sched& S, const Epi& E) {
;     ...
;             PG8_LDB(B0, 0, 0); PG8_LDB(B1, 0, 1); PG8_SCHED; PG8_LDA(At, 0, 0); PG8_STAGE(PG8_SA(1, 1), a1 + hstep, voffA);
;             PG8_WAIT_V(8); PG8_WAIT_L(0); PG8_BAR; PG8_MMA(0, 0, At, B0); PG8_MMA(0, 1, At, B1); PG8_BAR; PG8_SCHED;
;             PG8_LDA(At, 0, 1); PG8_STAGE(PG8_SB(0, 0), b2, voffB); PG8_STAGE(PG8_SB(0, 1), b2 + hstep, voffB); PG8_STAGE(PG8_SA(0, 0), a2, voffA);
;             PG8_WAIT_V(8); PG8_WAIT_L(0); PG8_BAR; PG8_MMA(1, 0, At, B0); PG8_MMA(1, 1, At, B1); PG8_BAR; PG8_SCHED;
	s_waitcnt lgkmcnt(0)
	v_mfma_f32_16x16x32_bf16 v[128:131], v[142:145], v[192:195], v[128:131]
	v_mfma_f32_16x16x32_bf16 v[124:127], v[156:159], v[192:195], v[124:127]
	v_mfma_f32_16x16x32_bf16 v[112:115], v[142:145], v[200:203], v[112:115]
	v_mfma_f32_16x16x32_bf16 v[108:111], v[156:159], v[200:203], v[108:111]
	v_mfma_f32_16x16x32_bf16 v[96:99], v[142:145], v[216:219], v[96:99]
	v_mfma_f32_16x16x32_bf16 v[92:95], v[156:159], v[216:219], v[92:95]
	v_mfma_f32_16x16x32_bf16 v[80:83], v[142:145], v[224:227], v[80:83]
	v_mfma_f32_16x16x32_bf16 v[76:79], v[156:159], v[224:227], v[76:79]
	v_mfma_f32_16x16x32_bf16 v[128:131], v[146:149], v[196:199], v[128:131]
	v_mfma_f32_16x16x32_bf16 v[124:127], v[172:175], v[196:199], v[124:127]
	v_mfma_f32_16x16x32_bf16 v[112:115], v[146:149], v[212:215], v[112:115]
	v_mfma_f32_16x16x32_bf16 v[108:111], v[172:175], v[212:215], v[108:111]
	v_mfma_f32_16x16x32_bf16 v[96:99], v[146:149], v[220:223], v[96:99]
	v_mfma_f32_16x16x32_bf16 v[92:95], v[172:175], v[220:223], v[92:95]
	v_mfma_f32_16x16x32_bf16 v[80:83], v[146:149], v[228:231], v[80:83]
	v_mfma_f32_16x16x32_bf16 v[76:79], v[172:175], v[228:231], v[76:79]
	v_mfma_f32_16x16x32_bf16 v[120:123], v[176:179], v[192:195], v[120:123]
	v_mfma_f32_16x16x32_bf16 v[116:119], v[184:187], v[192:195], v[116:119]
	v_mfma_f32_16x16x32_bf16 v[104:107], v[176:179], v[200:203], v[104:107]
	v_mfma_f32_16x16x32_bf16 v[100:103], v[184:187], v[200:203], v[100:103]
	v_mfma_f32_16x16x32_bf16 v[88:91], v[176:179], v[216:219], v[88:91]
	v_mfma_f32_16x16x32_bf16 v[84:87], v[184:187], v[216:219], v[84:87]
	v_mfma_f32_16x16x32_bf16 v[72:75], v[176:179], v[224:227], v[72:75]
	v_mfma_f32_16x16x32_bf16 v[68:71], v[184:187], v[224:227], v[68:71]
	v_mfma_f32_16x16x32_bf16 v[120:123], v[180:183], v[196:199], v[120:123]
	v_mfma_f32_16x16x32_bf16 v[116:119], v[188:191], v[196:199], v[116:119]
	v_mfma_f32_16x16x32_bf16 v[104:107], v[180:183], v[212:215], v[104:107]
	v_mfma_f32_16x16x32_bf16 v[100:103], v[188:191], v[212:215], v[100:103]
	v_mfma_f32_16x16x32_bf16 v[88:91], v[180:183], v[220:223], v[88:91]
	v_mfma_f32_16x16x32_bf16 v[84:87], v[188:191], v[220:223], v[84:87]
	v_mfma_f32_16x16x32_bf16 v[72:75], v[180:183], v[228:231], v[72:75]
	v_mfma_f32_16x16x32_bf16 v[68:71], v[188:191], v[228:231], v[68:71]
	s_barrier
	s_add_i32 s56, s57, s42
	s_add_u32 s98, s36, 0x80
	s_addc_u32 s99, s37, 0
	s_mov_b32 m0, s56
	ds_read_b128 v[192:195], v154 offset:16384
	ds_read_b128 v[196:199], v154 offset:17408
	ds_read_b128 v[200:203], v154 offset:18432
	ds_read_b128 v[212:215], v154 offset:19456
	ds_read_b128 v[216:219], v154 offset:20480
	ds_read_b128 v[220:223], v154 offset:21504
	ds_read_b128 v[224:227], v154 offset:22528
	ds_read_b128 v[228:231], v154 offset:23552
	global_load_lds_dwordx4 v134, s[36:37]
	s_add_i32 m0, s56, 0x2000
	s_add_u32 s56, s36, 0x80000
	s_addc_u32 s57, s37, 0
	s_add_i32 s55, s55, s42
	global_load_lds_dwordx4 v0, s[36:37]
	s_mov_b32 m0, s55
	s_add_u32 s100, s40, 0x80
	s_addc_u32 s101, s41, 0
	s_nop 0
	global_load_lds_dwordx4 v134, s[56:57]
	s_add_i32 m0, s55, 0x2000
	s_nop 0
	global_load_lds_dwordx4 v0, s[56:57]
	s_mov_b32 m0, s43
	s_nop 0
	global_load_lds_dwordx4 v136, s[40:41]
	s_mov_b32 m0, s46
	s_nop 0
	global_load_lds_dwordx4 v132, s[40:41]
	s_waitcnt vmcnt(8)
	s_waitcnt lgkmcnt(0)
	s_barrier
	s_waitcnt lgkmcnt(0)
	v_mfma_f32_16x16x32_bf16 v[64:67], v[142:145], v[192:195], v[64:67]
	v_mfma_f32_16x16x32_bf16 v[60:63], v[156:159], v[192:195], v[60:63]
	v_mfma_f32_16x16x32_bf16 v[48:51], v[142:145], v[200:203], v[48:51]
	v_mfma_f32_16x16x32_bf16 v[44:47], v[156:159], v[200:203], v[44:47]
	v_mfma_f32_16x16x32_bf16 v[32:35], v[142:145], v[216:219], v[32:35]
	v_mfma_f32_16x16x32_bf16 v[28:31], v[156:159], v[216:219], v[28:31]
	v_mfma_f32_16x16x32_bf16 v[16:19], v[142:145], v[224:227], v[16:19]
	v_mfma_f32_16x16x32_bf16 v[12:15], v[156:159], v[224:227], v[12:15]
	v_mfma_f32_16x16x32_bf16 v[64:67], v[146:149], v[196:199], v[64:67]
	v_mfma_f32_16x16x32_bf16 v[60:63], v[172:175], v[196:199], v[60:63]
	v_mfma_f32_16x16x32_bf16 v[48:51], v[146:149], v[212:215], v[48:51]
	v_mfma_f32_16x16x32_bf16 v[44:47], v[172:175], v[212:215], v[44:47]
	v_mfma_f32_16x16x32_bf16 v[32:35], v[146:149], v[220:223], v[32:35]
	v_mfma_f32_16x16x32_bf16 v[28:31], v[172:175], v[220:223], v[28:31]
	v_mfma_f32_16x16x32_bf16 v[16:19], v[146:149], v[228:231], v[16:19]
	v_mfma_f32_16x16x32_bf16 v[12:15], v[172:175], v[228:231], v[12:15]
	v_mfma_f32_16x16x32_bf16 v[56:59], v[176:179], v[192:195], v[56:59]
	v_mfma_f32_16x16x32_bf16 v[52:55], v[184:187], v[192:195], v[52:55]
	v_mfma_f32_16x16x32_bf16 v[40:43], v[176:179], v[200:203], v[40:43]
	v_mfma_f32_16x16x32_bf16 v[36:39], v[184:187], v[200:203], v[36:39]
	v_mfma_f32_16x16x32_bf16 v[24:27], v[176:179], v[216:219], v[24:27]
	v_mfma_f32_16x16x32_bf16 v[20:23], v[184:187], v[216:219], v[20:23]
	v_mfma_f32_16x16x32_bf16 v[8:11], v[176:179], v[224:227], v[8:11]
	v_mfma_f32_16x16x32_bf16 v[4:7], v[184:187], v[224:227], v[4:7]
	v_mfma_f32_16x16x32_bf16 v[56:59], v[180:183], v[196:199], v[56:59]
	v_mfma_f32_16x16x32_bf16 v[52:55], v[188:191], v[196:199], v[52:55]
	v_mfma_f32_16x16x32_bf16 v[40:43], v[180:183], v[212:215], v[40:43]
	v_mfma_f32_16x16x32_bf16 v[36:39], v[188:191], v[212:215], v[36:39]
	v_mfma_f32_16x16x32_bf16 v[24:27], v[180:183], v[220:223], v[24:27]
	v_mfma_f32_16x16x32_bf16 v[20:23], v[188:191], v[220:223], v[20:23]
	v_mfma_f32_16x16x32_bf16 v[8:11], v[180:183], v[228:231], v[8:11]
	v_mfma_f32_16x16x32_bf16 v[4:7], v[188:191], v[228:231], v[4:7]
	s_barrier
; #define PG8_STAGE(bufoff, gbase, voff) do { _Pragma("unroll") for (int _i = 0; _i < 2; ++_i) \
;         __builtin_amdgcn_global_load_lds((const unsigned*)((const char*)(gbase) + (voff)[_i]), (PG8_LAS unsigned*)(lds + (bufoff) + ldsw + _i * 8192), 16, 0, 0); } while (0)
; #define PG8_LDA(dst, b, h) do { _Pragma("unroll") for (int m = 0; m < 4; ++m) _Pragma("unroll") for (int k = 0; k < 2; ++k) dst[m][k] = *(const PG8_LAS bf16x8*)(lds + PG8_SA(b, h) + aoff + m * 2048 + k * 1024); } while (0)
; #define PG8_LDB(dst, b, h) do { _Pragma("unroll") for (int n = 0; n < 2; ++n) _Pragma("unroll") for (int k = 0; k < 2; ++k) dst[n][k] = *(const PG8_LAS bf16x8*)(lds + PG8_SB(b, h) + boff + n * 2048 + k * 1024); } while (0)
; #define PG8_MMA(ai, bj, At, Bt) do { __builtin_amdgcn_s_setprio(1); _Pragma("unroll") for (int m = 0; m < 4; ++m) _Pragma("unroll") for (int n = 0; n < 2; ++n) _Pragma("unroll") for (int k = 0; k < 2; ++k) \
;         acc[ai][bj][m][n] = __builtin_amdgcn_mfma_f32_16x16x32_bf16(Bt[n][k], At[m][k], acc[ai][bj][m][n], 0, 0, 0); __builtin_amdgcn_s_setprio(0); } while (0)
; #define PG8_WAIT_V(n) asm volatile("s_waitcnt vmcnt(" #n ")" ::: "memory")
; #define PG8_WAIT_L(n) asm volatile("s_waitcnt lgkmcnt(" #n ")" ::: "memory")
; #define PG8_BAR __builtin_amdgcn_s_barrier()
; #define PG8_SCHED __builtin_amdgcn_sched_barrier(0)
; template <class Epi, class Sched, bool ALIGN_EPI = false, bool SP2 = false>
; __device__ __forceinline__ void gemm_phase(PG8_LAS unsigned char* lds, const Gemm g, const Sched& S, const Epi& E) {
;     ...
;             PG8_WAIT_V(8); PG8_WAIT_L(0); PG8_BAR; PG8_MMA(1, 0, At, B0); PG8_MMA(1, 1, At, B1); PG8_BAR; PG8_SCHED;
;             PG8_LDB(B0, 1, 0); PG8_LDB(B1, 1, 1); PG8_SCHED; PG8_LDA(At, 1, 0); PG8_STAGE(PG8_SA(0, 1), a2 + hstep, voffA);
;             PG8_WAIT_V(8); PG8_WAIT_L(0); PG8_BAR; PG8_MMA(0, 0, At, B0); PG8_MMA(0, 1, At, B1); PG8_BAR; PG8_SCHED;
;             PG8_LDA(At, 1, 1); PG8_STAGE(PG8_SB(1, 0), b3, voffB); PG8_STAGE(PG8_SB(1, 1), b3 + hstep, voffB); PG8_STAGE(PG8_SA(1, 0), a3, voffA);
;             PG8_WAIT_V(8); PG8_WAIT_L(0); PG8_BAR; PG8_MMA(1, 0, At, B0); PG8_MMA(1, 1, At, B1); PG8_BAR; PG8_SCHED;
	s_add_i32 s55, 0, 0x18000
	s_add_i32 s56, 0, 0x1c000
	ds_read_b128 v[142:145], v170
	ds_read_b128 v[146:149], v170 offset:1024
	ds_read_b128 v[156:159], v170 offset:2048
	ds_read_b128 v[172:175], v170 offset:3072
	ds_read_b128 v[176:179], v171
	ds_read_b128 v[180:183], v171 offset:1024
	ds_read_b128 v[184:187], v171 offset:2048
	ds_read_b128 v[188:191], v171 offset:3072
	s_add_u32 s40, s40, 0x80000
	s_addc_u32 s41, s41, 0
	s_mov_b32 m0, s47
	ds_read_b128 v[192:195], v154 offset:32768
	ds_read_b128 v[196:199], v154 offset:33792
	ds_read_b128 v[200:203], v154 offset:34816
	ds_read_b128 v[212:215], v154 offset:35840
	ds_read_b128 v[216:219], v154 offset:36864
	ds_read_b128 v[220:223], v154 offset:37888
	ds_read_b128 v[224:227], v154 offset:38912
	ds_read_b128 v[228:231], v154 offset:39936
	global_load_lds_dwordx4 v136, s[40:41]
	s_mov_b32 m0, s48
	s_nop 0
	global_load_lds_dwordx4 v132, s[40:41]
	s_waitcnt vmcnt(8)
	s_waitcnt lgkmcnt(0)
	s_barrier
	s_waitcnt lgkmcnt(0)
	v_mfma_f32_16x16x32_bf16 v[128:131], v[142:145], v[192:195], v[128:131]
	v_mfma_f32_16x16x32_bf16 v[124:127], v[156:159], v[192:195], v[124:127]
	v_mfma_f32_16x16x32_bf16 v[112:115], v[142:145], v[200:203], v[112:115]
	v_mfma_f32_16x16x32_bf16 v[108:111], v[156:159], v[200:203], v[108:111]
	v_mfma_f32_16x16x32_bf16 v[96:99], v[142:145], v[216:219], v[96:99]
	v_mfma_f32_16x16x32_bf16 v[92:95], v[156:159], v[216:219], v[92:95]
	v_mfma_f32_16x16x32_bf16 v[80:83], v[142:145], v[224:227], v[80:83]
	v_mfma_f32_16x16x32_bf16 v[76:79], v[156:159], v[224:227], v[76:79]
	v_mfma_f32_16x16x32_bf16 v[128:131], v[146:149], v[196:199], v[128:131]
	v_mfma_f32_16x16x32_bf16 v[124:127], v[172:175], v[196:199], v[124:127]
	v_mfma_f32_16x16x32_bf16 v[112:115], v[146:149], v[212:215], v[112:115]
	v_mfma_f32_16x16x32_bf16 v[108:111], v[172:175], v[212:215], v[108:111]
	v_mfma_f32_16x16x32_bf16 v[96:99], v[146:149], v[220:223], v[96:99]
	v_mfma_f32_16x16x32_bf16 v[92:95], v[172:175], v[220:223], v[92:95]
	v_mfma_f32_16x16x32_bf16 v[80:83], v[146:149], v[228:231], v[80:83]
	v_mfma_f32_16x16x32_bf16 v[76:79], v[172:175], v[228:231], v[76:79]
	v_mfma_f32_16x16x32_bf16 v[120:123], v[176:179], v[192:195], v[120:123]
	v_mfma_f32_16x16x32_bf16 v[116:119], v[184:187], v[192:195], v[116:119]
	v_mfma_f32_16x16x32_bf16 v[104:107], v[176:179], v[200:203], v[104:107]
	v_mfma_f32_16x16x32_bf16 v[100:103], v[184:187], v[200:203], v[100:103]
	v_mfma_f32_16x16x32_bf16 v[88:91], v[176:179], v[216:219], v[88:91]
	v_mfma_f32_16x16x32_bf16 v[84:87], v[184:187], v[216:219], v[84:87]
	v_mfma_f32_16x16x32_bf16 v[72:75], v[176:179], v[224:227], v[72:75]
	v_mfma_f32_16x16x32_bf16 v[68:71], v[184:187], v[224:227], v[68:71]
	v_mfma_f32_16x16x32_bf16 v[120:123], v[180:183], v[196:199], v[120:123]
	v_mfma_f32_16x16x32_bf16 v[116:119], v[188:191], v[196:199], v[116:119]
	v_mfma_f32_16x16x32_bf16 v[104:107], v[180:183], v[212:215], v[104:107]
	v_mfma_f32_16x16x32_bf16 v[100:103], v[188:191], v[212:215], v[100:103]
	v_mfma_f32_16x16x32_bf16 v[88:91], v[180:183], v[220:223], v[88:91]
	v_mfma_f32_16x16x32_bf16 v[84:87], v[188:191], v[220:223], v[84:87]
	v_mfma_f32_16x16x32_bf16 v[72:75], v[180:183], v[228:231], v[72:75]
	v_mfma_f32_16x16x32_bf16 v[68:71], v[188:191], v[228:231], v[68:71]
	s_barrier
	s_add_i32 s40, s55, s42
	s_mov_b32 m0, s40
	ds_read_b128 v[192:195], v154 offset:49152
	ds_read_b128 v[196:199], v154 offset:50176
	ds_read_b128 v[200:203], v154 offset:51200
	ds_read_b128 v[212:215], v154 offset:52224
	ds_read_b128 v[216:219], v154 offset:53248
	ds_read_b128 v[220:223], v154 offset:54272
	ds_read_b128 v[224:227], v154 offset:55296
	ds_read_b128 v[228:231], v154 offset:56320
	global_load_lds_dwordx4 v134, s[98:99]
	s_add_i32 m0, s40, 0x2000
	s_add_u32 s36, s36, 0x80080
	s_addc_u32 s37, s37, 0
	s_add_i32 s40, s56, s42
	global_load_lds_dwordx4 v0, s[98:99]
	s_mov_b32 m0, s40
	s_nop 0
	global_load_lds_dwordx4 v134, s[36:37]
	s_add_i32 m0, s40, 0x2000
	s_nop 0
	global_load_lds_dwordx4 v0, s[36:37]
	s_mov_b32 m0, s49
	s_nop 0
	global_load_lds_dwordx4 v136, s[100:101]
	s_mov_b32 m0, s50
	s_nop 0
	global_load_lds_dwordx4 v132, s[100:101]
	s_waitcnt vmcnt(8)
	s_waitcnt lgkmcnt(0)
	s_barrier
	s_waitcnt lgkmcnt(0)
	v_mfma_f32_16x16x32_bf16 v[64:67], v[142:145], v[192:195], v[64:67]
	v_mfma_f32_16x16x32_bf16 v[60:63], v[156:159], v[192:195], v[60:63]
	v_mfma_f32_16x16x32_bf16 v[48:51], v[142:145], v[200:203], v[48:51]
	v_mfma_f32_16x16x32_bf16 v[44:47], v[156:159], v[200:203], v[44:47]
	v_mfma_f32_16x16x32_bf16 v[32:35], v[142:145], v[216:219], v[32:35]
	v_mfma_f32_16x16x32_bf16 v[28:31], v[156:159], v[216:219], v[28:31]
	v_mfma_f32_16x16x32_bf16 v[16:19], v[142:145], v[224:227], v[16:19]
	v_mfma_f32_16x16x32_bf16 v[12:15], v[156:159], v[224:227], v[12:15]
	v_mfma_f32_16x16x32_bf16 v[64:67], v[146:149], v[196:199], v[64:67]
	v_mfma_f32_16x16x32_bf16 v[60:63], v[172:175], v[196:199], v[60:63]
	v_mfma_f32_16x16x32_bf16 v[48:51], v[146:149], v[212:215], v[48:51]
	v_mfma_f32_16x16x32_bf16 v[44:47], v[172:175], v[212:215], v[44:47]
	v_mfma_f32_16x16x32_bf16 v[32:35], v[146:149], v[220:223], v[32:35]
	v_mfma_f32_16x16x32_bf16 v[28:31], v[172:175], v[220:223], v[28:31]
	v_mfma_f32_16x16x32_bf16 v[16:19], v[146:149], v[228:231], v[16:19]
	v_mfma_f32_16x16x32_bf16 v[12:15], v[172:175], v[228:231], v[12:15]
	v_mfma_f32_16x16x32_bf16 v[56:59], v[176:179], v[192:195], v[56:59]
	v_mfma_f32_16x16x32_bf16 v[52:55], v[184:187], v[192:195], v[52:55]
	v_mfma_f32_16x16x32_bf16 v[40:43], v[176:179], v[200:203], v[40:43]
	v_mfma_f32_16x16x32_bf16 v[36:39], v[184:187], v[200:203], v[36:39]
	v_mfma_f32_16x16x32_bf16 v[24:27], v[176:179], v[216:219], v[24:27]
	v_mfma_f32_16x16x32_bf16 v[20:23], v[184:187], v[216:219], v[20:23]
	v_mfma_f32_16x16x32_bf16 v[8:11], v[176:179], v[224:227], v[8:11]
	v_mfma_f32_16x16x32_bf16 v[4:7], v[184:187], v[224:227], v[4:7]
	v_mfma_f32_16x16x32_bf16 v[56:59], v[180:183], v[196:199], v[56:59]
	v_mfma_f32_16x16x32_bf16 v[52:55], v[188:191], v[196:199], v[52:55]
	v_mfma_f32_16x16x32_bf16 v[40:43], v[180:183], v[212:215], v[40:43]
	v_mfma_f32_16x16x32_bf16 v[36:39], v[188:191], v[212:215], v[36:39]
	v_mfma_f32_16x16x32_bf16 v[24:27], v[180:183], v[220:223], v[24:27]
	v_mfma_f32_16x16x32_bf16 v[20:23], v[188:191], v[220:223], v[20:23]
	v_mfma_f32_16x16x32_bf16 v[8:11], v[180:183], v[228:231], v[8:11]
	v_mfma_f32_16x16x32_bf16 v[4:7], v[188:191], v[228:231], v[4:7]
	s_barrier
	s_add_i32 s54, s54, 2
	s_add_u32 s2, s2, 0x100
	s_addc_u32 s3, s3, 0
	s_cmp_gt_u32 s54, 29
	s_cbranch_scc0 .LBB0_174
	s_and_b64 vcc, exec, s[10:11]
	s_cbranch_vccz .LBB0_177
	s_barrier
; __device__ __forceinline__ float ss_get(const ss_t* p) { const ss_t v = *p; return (float)(unsigned)(v >> 32) + (float)(unsigned)v * 2.3283064365386963e-10f; }
; __device__ __forceinline__ f32x2 gelu_pk(f32x2 v) {
;     const f32x2 av = __builtin_elementwise_abs(v), d = av * 0.2316418882f + 1.0f;
;     f32x2 t; t.x = __builtin_amdgcn_rcpf(d.x); t.y = __builtin_amdgcn_rcpf(d.y);
;     f32x2 q = t * 0.5307027145f + (-0.7265760135f); q = q * t + 0.7107068705f; q = q * t + (-0.142248368f); q = q * t + 0.127414796f; q = q * t;
;     const f32x2 s = (v * v) * (-0.72134752044f);
;     f32x2 e; e.x = __builtin_amdgcn_exp2f(s.x); e.y = __builtin_amdgcn_exp2f(s.y);
;     const f32x2 m = v * (q * e), r = v - m;
;     f32x2 o; o.x = v.x < 0.f ? m.x : r.x; o.y = v.y < 0.f ? m.y : r.y; return o;
; }
;     __device__ __forceinline__ void operator()(const f32x4 (&acc)[2][2][4][2], const Unit& u, int wr, int wc, int fr, int fq) const {
;         int row0 = u.pm * BM + wr * 64 + fr; asm volatile("" : "+v"(row0));     const int col0 = u.pn * BM + wc * 32 + 8 * fq; const bool act = u.pn < gelu_tiles;
; #pragma unroll
;         for (int ai = 0; ai < 2; ++ai)
; #pragma unroll
;             for (int m = 0; m < 4; ++m) { const int row = row0 + ai * HALF + m * 16; bf16_t* rowp = O + (size_t)row * ldc + col0;
;                 const float rs = 1.0f / sqrtf(ss_get(ssq + row) * (1.0f / 2048.f) + 1e-6f);
; #pragma unroll
;                 for (int bj = 0; bj < 2; ++bj) { f32x4 v0 = acc[ai][bj][m][0] * rs, v1 = acc[ai][bj][m][1] * rs;
;                     if (act) { f32x2 a = gelu_pk((f32x2){v0[0], v0[1]}), b = gelu_pk((f32x2){v0[2], v0[3]}), c = gelu_pk((f32x2){v1[0], v1[1]}), d = gelu_pk((f32x2){v1[2], v1[3]});
;                         v0 = (f32x4){a.x, a.y, b.x, b.y}; v1 = (f32x4){c.x, c.y, d.x, d.y}; }
.LBB0_177:
	s_setprio 0
	v_mov_b32_e32 v142, v152
	s_cmp_lt_i32 s53, 8
	v_ashrrev_i32_e32 v143, 31, v142
	v_lshl_add_u64 v[144:145], v[142:143], 3, s[4:5]
	s_flbit_i32_b32 s2, 0
	v_mov_b32_e32 v149, v2
	s_cselect_b64 s[40:41], -1, 0
	s_min_u32 s15, s2, 32
	s_sub_i32 s52, 32, s15
	s_cmp_gt_i32 s53, 7
	v_mov_b32_e32 v146, v240
	s_nop 1
	s_nop 0
	s_nop 1
	s_nop 1
	s_nop 1
	v_pk_mul_f32 v[130:131], v[130:131], v[146:147] op_sel_hi:[1,0]
	v_pk_mul_f32 v[128:129], v[128:129], v[146:147] op_sel_hi:[1,0]
	v_pk_mul_f32 v[148:149], v[126:127], v[146:147] op_sel_hi:[1,0]
	v_pk_mul_f32 v[150:151], v[124:125], v[146:147] op_sel_hi:[1,0]
	s_cbranch_scc1 .LBB0_179
	v_and_b32_e32 v125, 0x7fffffff, v129
	v_and_b32_e32 v124, 0x7fffffff, v128
	v_pk_fma_f32 v[124:125], v[124:125], s[90:91], 1.0 op_sel_hi:[1,0,0]
	s_mov_b32 s2, 0xbf3a00e3
	v_rcp_f32_e32 v126, v124
	v_rcp_f32_e32 v127, v125
	v_mov_b64_e32 v[124:125], s[2:3]
	v_pk_mul_f32 v[158:159], v[128:129], v[128:129]
	s_mov_b32 s2, 0xbf38aa3b
	v_pk_fma_f32 v[156:157], v[126:127], s[92:93], v[124:125] op_sel_hi:[1,0,0]
	v_pk_mul_f32 v[158:159], v[158:159], s[2:3] op_sel_hi:[1,0]
	v_pk_fma_f32 v[156:157], v[126:127], v[156:157], s[94:95] op_sel_hi:[1,1,0]
	v_exp_f32_e32 v158, v158
	v_exp_f32_e32 v159, v159
	v_pk_fma_f32 v[156:157], v[126:127], v[156:157], s[96:97] op_sel_hi:[1,1,0]
	v_cmp_gt_f32_e32 vcc, 0, v128
	v_pk_fma_f32 v[156:157], v[126:127], v[156:157], s[30:31] op_sel_hi:[1,1,0]
	s_nop 0
	v_pk_mul_f32 v[126:127], v[126:127], v[156:157]
	v_pk_mul_f32 v[156:157], v[130:131], v[130:131]
	v_pk_mul_f32 v[126:127], v[158:159], v[126:127]
	v_pk_mul_f32 v[156:157], v[156:157], s[2:3] op_sel_hi:[1,0]
	v_pk_mul_f32 v[158:159], v[128:129], v[126:127]
	v_pk_fma_f32 v[126:127], v[128:129], v[126:127], v[128:129] neg_lo:[1,0,0] neg_hi:[1,0,0]
	v_exp_f32_e32 v156, v156
	v_cndmask_b32_e32 v128, v126, v158, vcc
	v_cmp_gt_f32_e32 vcc, 0, v129
	v_and_b32_e32 v126, 0x7fffffff, v130
	v_exp_f32_e32 v157, v157
	v_cndmask_b32_e32 v129, v127, v159, vcc
	v_and_b32_e32 v127, 0x7fffffff, v131
	v_pk_fma_f32 v[126:127], v[126:127], s[90:91], 1.0 op_sel_hi:[1,0,0]
	v_cmp_gt_f32_e32 vcc, 0, v130
	v_rcp_f32_e32 v126, v126
	v_rcp_f32_e32 v127, v127
	s_nop 0
	v_pk_fma_f32 v[158:159], v[126:127], s[92:93], v[124:125] op_sel_hi:[1,0,0]
	s_nop 0
	v_pk_fma_f32 v[158:159], v[126:127], v[158:159], s[94:95] op_sel_hi:[1,1,0]
	s_nop 0
	v_pk_fma_f32 v[158:159], v[126:127], v[158:159], s[96:97] op_sel_hi:[1,1,0]
	s_nop 0
	v_pk_fma_f32 v[158:159], v[126:127], v[158:159], s[30:31] op_sel_hi:[1,1,0]
	s_nop 0
	v_pk_mul_f32 v[126:127], v[126:127], v[158:159]
	v_pk_mul_f32 v[158:159], v[150:151], v[150:151]
	v_pk_mul_f32 v[126:127], v[156:157], v[126:127]
	v_pk_mul_f32 v[158:159], v[158:159], s[2:3] op_sel_hi:[1,0]
	v_pk_mul_f32 v[156:157], v[130:131], v[126:127]
	v_pk_fma_f32 v[126:127], v[130:131], v[126:127], v[130:131] neg_lo:[1,0,0] neg_hi:[1,0,0]
	v_exp_f32_e32 v158, v158
	v_cndmask_b32_e32 v130, v126, v156, vcc
	v_cmp_gt_f32_e32 vcc, 0, v131
	v_and_b32_e32 v126, 0x7fffffff, v150
	v_exp_f32_e32 v159, v159
	v_cndmask_b32_e32 v131, v127, v157, vcc
	v_and_b32_e32 v127, 0x7fffffff, v151
	v_pk_fma_f32 v[126:127], v[126:127], s[90:91], 1.0 op_sel_hi:[1,0,0]
	v_cmp_gt_f32_e32 vcc, 0, v150
	v_rcp_f32_e32 v126, v126
	v_rcp_f32_e32 v127, v127
	s_nop 0
	v_pk_fma_f32 v[156:157], v[126:127], s[92:93], v[124:125] op_sel_hi:[1,0,0]
	s_nop 0
	v_pk_fma_f32 v[156:157], v[126:127], v[156:157], s[94:95] op_sel_hi:[1,1,0]
	s_nop 0
	v_pk_fma_f32 v[156:157], v[126:127], v[156:157], s[96:97] op_sel_hi:[1,1,0]
	s_nop 0
	v_pk_fma_f32 v[156:157], v[126:127], v[156:157], s[30:31] op_sel_hi:[1,1,0]
	s_nop 0
	v_pk_mul_f32 v[126:127], v[126:127], v[156:157]
	v_pk_mul_f32 v[156:157], v[148:149], v[148:149]
	v_pk_mul_f32 v[126:127], v[158:159], v[126:127]
	s_nop 0
	v_pk_mul_f32 v[158:159], v[150:151], v[126:127]
	v_pk_fma_f32 v[126:127], v[150:151], v[126:127], v[150:151] neg_lo:[1,0,0] neg_hi:[1,0,0]
	s_nop 0
	v_cndmask_b32_e32 v150, v126, v158, vcc
	v_cmp_gt_f32_e32 vcc, 0, v151
	v_and_b32_e32 v126, 0x7fffffff, v148
	s_nop 0
	v_cndmask_b32_e32 v151, v127, v159, vcc
	v_and_b32_e32 v127, 0x7fffffff, v149
	v_pk_fma_f32 v[126:127], v[126:127], s[90:91], 1.0 op_sel_hi:[1,0,0]
	v_cmp_gt_f32_e32 vcc, 0, v148
	v_rcp_f32_e32 v126, v126
	v_rcp_f32_e32 v127, v127
	s_nop 0
	v_pk_fma_f32 v[124:125], v[126:127], s[92:93], v[124:125] op_sel_hi:[1,0,0]
	s_nop 0
	v_pk_fma_f32 v[124:125], v[126:127], v[124:125], s[94:95] op_sel_hi:[1,1,0]
	s_nop 0
	v_pk_fma_f32 v[124:125], v[126:127], v[124:125], s[96:97] op_sel_hi:[1,1,0]
	s_nop 0
	v_pk_fma_f32 v[124:125], v[126:127], v[124:125], s[30:31] op_sel_hi:[1,1,0]
	s_nop 0
	v_pk_mul_f32 v[124:125], v[126:127], v[124:125]
	v_pk_mul_f32 v[126:127], v[156:157], s[2:3] op_sel_hi:[1,0]
	s_nop 0
	v_exp_f32_e32 v126, v126
	v_exp_f32_e32 v127, v127
	s_nop 0
	v_pk_mul_f32 v[124:125], v[126:127], v[124:125]
	s_nop 0
	v_pk_mul_f32 v[126:127], v[148:149], v[124:125]
	v_pk_fma_f32 v[124:125], v[148:149], v[124:125], v[148:149] neg_lo:[1,0,0] neg_hi:[1,0,0]
	s_nop 0
	v_cndmask_b32_e32 v148, v124, v126, vcc
	v_cmp_gt_f32_e32 vcc, 0, v149
	s_nop 1
	v_cndmask_b32_e32 v149, v125, v127, vcc

; template <class Epi, class Sched, bool ALIGN_EPI = false, bool SP2 = false>
; __device__ __forceinline__ void gemm_phase(PG8_LAS unsigned char* lds, const Gemm g, const Sched& S, const Epi& E) {
;     ...
; #pragma unroll
;         for (int a = 0; a < 2; ++a)
; #pragma unroll
;             for (int b = 0; b < 2; ++b)
; #pragma unroll
;                 for (int m = 0; m < 4; ++m)
; #pragma unroll
;                     for (int n = 0; n < 2; ++n) acc[a][b][m][n] = (f32x4){0.f, 0.f, 0.f, 0.f};
;         cur = nxt; cA = nA; cB = nB; ++ui;
.LBB0_925:
	s_add_i32 s59, s59, 1
	s_mov_b64 s[2:3], s[10:11]
	s_lshl_b32 s10, s59, 3
	v_readlane_b32 s16, v248, 25
	s_mov_b32 s60, s42
	s_add_i32 s42, s10, s16
	s_cmp_lt_i32 s42, 8
	s_cselect_b64 s[44:45], -1, 0
	s_ashr_i32 s43, s42, 31
	s_lshl_b64 s[10:11], s[42:43], 20
	s_add_u32 s10, s52, s10
	s_addc_u32 s11, s53, s11
	v_mov_b32_e32 v3, v2
	s_and_b64 s[46:47], s[44:45], exec
	v_mov_b32_e32 v0, v2
	s_waitcnt lgkmcnt(0)
	v_mov_b32_e32 v1, v2
	v_mov_b64_e32 v[6:7], v[2:3]
	v_mov_b64_e32 v[10:11], v[2:3]
	v_mov_b64_e32 v[22:23], v[2:3]
	v_mov_b64_e32 v[26:27], v[2:3]
	v_mov_b64_e32 v[38:39], v[2:3]
	v_mov_b64_e32 v[42:43], v[2:3]
	v_mov_b64_e32 v[54:55], v[2:3]
	v_mov_b64_e32 v[58:59], v[2:3]
	v_mov_b64_e32 v[14:15], v[2:3]
	v_mov_b64_e32 v[18:19], v[2:3]
	v_mov_b64_e32 v[30:31], v[2:3]
	v_mov_b64_e32 v[34:35], v[2:3]
	v_mov_b64_e32 v[46:47], v[2:3]
	v_mov_b64_e32 v[50:51], v[2:3]
	v_mov_b64_e32 v[62:63], v[2:3]
	v_mov_b64_e32 v[66:67], v[2:3]
	v_mov_b64_e32 v[70:71], v[2:3]
	v_mov_b64_e32 v[74:75], v[2:3]
	v_mov_b64_e32 v[86:87], v[2:3]
	v_mov_b64_e32 v[90:91], v[2:3]
	v_mov_b64_e32 v[102:103], v[2:3]
	v_mov_b64_e32 v[106:107], v[2:3]
	v_mov_b64_e32 v[118:119], v[2:3]
	v_mov_b64_e32 v[122:123], v[2:3]
	v_mov_b64_e32 v[78:79], v[2:3]
	v_mov_b64_e32 v[82:83], v[2:3]
	v_mov_b64_e32 v[94:95], v[2:3]
	v_mov_b64_e32 v[98:99], v[2:3]
	v_mov_b64_e32 v[110:111], v[2:3]
	v_mov_b64_e32 v[114:115], v[2:3]
	v_mov_b64_e32 v[126:127], v[2:3]
	v_mov_b64_e32 v[130:131], v[2:3]
	s_cselect_b32 s43, s11, s3
	s_cselect_b32 s61, s10, s2
	s_mov_b32 s66, -2
	s_mov_b64 s[46:47], 0
	v_mov_b64_e32 v[4:5], v[0:1]
	v_mov_b64_e32 v[8:9], v[0:1]
	v_mov_b64_e32 v[20:21], v[0:1]
	v_mov_b64_e32 v[24:25], v[0:1]
	v_mov_b64_e32 v[36:37], v[0:1]
	v_mov_b64_e32 v[40:41], v[0:1]
	v_mov_b64_e32 v[52:53], v[0:1]
	v_mov_b64_e32 v[56:57], v[0:1]
	v_mov_b64_e32 v[12:13], v[0:1]
	v_mov_b64_e32 v[16:17], v[0:1]
	v_mov_b64_e32 v[28:29], v[0:1]
	v_mov_b64_e32 v[32:33], v[0:1]
	v_mov_b64_e32 v[44:45], v[0:1]
	v_mov_b64_e32 v[48:49], v[0:1]
	v_mov_b64_e32 v[60:61], v[0:1]
	v_mov_b64_e32 v[64:65], v[0:1]
	v_mov_b64_e32 v[68:69], v[0:1]
	v_mov_b64_e32 v[72:73], v[0:1]
	v_mov_b64_e32 v[84:85], v[0:1]
	v_mov_b64_e32 v[88:89], v[0:1]
	v_mov_b64_e32 v[100:101], v[0:1]
	v_mov_b64_e32 v[104:105], v[0:1]
	v_mov_b64_e32 v[116:117], v[0:1]
	v_mov_b64_e32 v[120:121], v[0:1]
	v_mov_b64_e32 v[76:77], v[0:1]
	v_mov_b64_e32 v[80:81], v[0:1]
	v_mov_b64_e32 v[92:93], v[0:1]
	v_mov_b64_e32 v[96:97], v[0:1]
	v_mov_b64_e32 v[108:109], v[0:1]
	v_mov_b64_e32 v[112:113], v[0:1]
	v_mov_b64_e32 v[124:125], v[0:1]
	v_mov_b64_e32 v[128:129], v[0:1]
	v_readlane_b32 s17, v248, 26
	v_add_u32_e32 v168, 0x10000, v192
	v_add_u32_e32 v169, 0x14000, v192
	v_add_u32_e32 v170, 0x18000, v192
	v_add_u32_e32 v171, 0x1c000, v192
	s_cmp_lg_u64 s[14:15], 0
	s_cbranch_scc1 .Lprio_P3
	s_setprio 1

; #define PG8_STAGE(bufoff, gbase, voff) do { _Pragma("unroll") for (int _i = 0; _i < 2; ++_i) \
;         __builtin_amdgcn_global_load_lds((const unsigned*)((const char*)(gbase) + (voff)[_i]), (PG8_LAS unsigned*)(lds + (bufoff) + ldsw + _i * 8192), 16, 0, 0); } while (0)
; #define PG8_LDA(dst, b, h) do { _Pragma("unroll") for (int m = 0; m < 4; ++m) _Pragma("unroll") for (int k = 0; k < 2; ++k) dst[m][k] = *(const PG8_LAS bf16x8*)(lds + PG8_SA(b, h) + aoff + m * 2048 + k * 1024); } while (0)
; #define PG8_LDB(dst, b, h) do { _Pragma("unroll") for (int n = 0; n < 2; ++n) _Pragma("unroll") for (int k = 0; k < 2; ++k) dst[n][k] = *(const PG8_LAS bf16x8*)(lds + PG8_SB(b, h) + boff + n * 2048 + k * 1024); } while (0)
; #define PG8_MMA(ai, bj, At, Bt) do { __builtin_amdgcn_s_setprio(1); _Pragma("unroll") for (int m = 0; m < 4; ++m) _Pragma("unroll") for (int n = 0; n < 2; ++n) _Pragma("unroll") for (int k = 0; k < 2; ++k) \
;         acc[ai][bj][m][n] = __builtin_amdgcn_mfma_f32_16x16x32_bf16(Bt[n][k], At[m][k], acc[ai][bj][m][n], 0, 0, 0); __builtin_amdgcn_s_setprio(0); } while (0)
; #define PG8_WAIT_V(n) asm volatile("s_waitcnt vmcnt(" #n ")" ::: "memory")
; #define PG8_WAIT_L(n) asm volatile("s_waitcnt lgkmcnt(" #n ")" ::: "memory")
; #define PG8_BAR __builtin_amdgcn_s_barrier()
; #define PG8_SCHED __builtin_amdgcn_sched_barrier(0)
; template <class Epi, class Sched, bool ALIGN_EPI = false, bool SP2 = false>
; __device__ __forceinline__ void gemm_phase(PG8_LAS unsigned char* lds, const Gemm g, const Sched& S, const Epi& E) {
;     ...
;             PG8_LDB(B0, 0, 0); PG8_LDB(B1, 0, 1); PG8_SCHED; PG8_LDA(At, 0, 0); PG8_STAGE(PG8_SA(1, 1), a1 + hstep, voffA);
;             PG8_WAIT_V(8); PG8_WAIT_L(0); PG8_BAR; PG8_MMA(0, 0, At, B0); PG8_MMA(0, 1, At, B1); PG8_BAR; PG8_SCHED;
;             PG8_LDA(At, 0, 1); PG8_STAGE(PG8_SB(0, 0), b2, voffB); PG8_STAGE(PG8_SB(0, 1), b2 + hstep, voffB); PG8_STAGE(PG8_SA(0, 0), a2, voffA);
;             PG8_WAIT_V(8); PG8_WAIT_L(0); PG8_BAR; PG8_MMA(1, 0, At, B0); PG8_MMA(1, 1, At, B1); PG8_BAR; PG8_SCHED;
.LBB0_926:
	s_add_u32 s2, s31, s46
	s_addc_u32 s3, s91, s47
	s_add_u32 s2, s2, 0x1ba00100
	s_addc_u32 s3, s3, 0
	s_add_u32 s67, s36, s46
	s_addc_u32 s68, s37, s47
	s_cmpk_eq_i32 s46, 0xf00
	s_cselect_b32 s49, s89, s3
	s_cselect_b32 s48, s88, s2
	s_cselect_b32 s3, s43, s68
	s_cselect_b32 s2, s61, s67
	s_add_i32 s67, 0, 0x10000
	s_add_i32 s70, 0, 0x14000
	ds_read_b128 v[132:135], v168
	ds_read_b128 v[136:139], v168 offset:1024
	ds_read_b128 v[140:143], v168 offset:2048
	ds_read_b128 v[144:147], v168 offset:3072
	ds_read_b128 v[148:151], v169
	ds_read_b128 v[152:155], v169 offset:1024
	ds_read_b128 v[180:183], v169 offset:2048
	ds_read_b128 v[184:187], v169 offset:3072
	v_lshl_add_u64 v[0:1], v[176:177], 0, s[46:47]
	s_add_i32 m0, s51, 0xc000
	ds_read_b128 v[188:191], v195
	ds_read_b128 v[196:199], v195 offset:1024
	ds_read_b128 v[200:203], v195 offset:2048
	ds_read_b128 v[212:215], v195 offset:3072
	ds_read_b128 v[216:219], v195 offset:4096
	ds_read_b128 v[220:223], v195 offset:5120
	ds_read_b128 v[224:227], v195 offset:6144
	ds_read_b128 v[228:231], v195 offset:7168
	global_load_lds_dwordx4 v[0:1], off
	v_lshl_add_u64 v[0:1], v[178:179], 0, s[46:47]
	s_add_i32 m0, s51, 0xe000
	s_nop 0
	global_load_lds_dwordx4 v[0:1], off
	s_waitcnt vmcnt(8)
	s_waitcnt lgkmcnt(0)
	s_barrier
	s_waitcnt lgkmcnt(0)
	v_mfma_f32_16x16x32_bf16 v[128:131], v[132:135], v[188:191], v[128:131]
	v_mfma_f32_16x16x32_bf16 v[124:127], v[140:143], v[188:191], v[124:127]
	v_mfma_f32_16x16x32_bf16 v[112:115], v[132:135], v[200:203], v[112:115]
	v_mfma_f32_16x16x32_bf16 v[108:111], v[140:143], v[200:203], v[108:111]
	v_mfma_f32_16x16x32_bf16 v[96:99], v[132:135], v[216:219], v[96:99]
	v_mfma_f32_16x16x32_bf16 v[92:95], v[140:143], v[216:219], v[92:95]
	v_mfma_f32_16x16x32_bf16 v[80:83], v[132:135], v[224:227], v[80:83]
	v_mfma_f32_16x16x32_bf16 v[76:79], v[140:143], v[224:227], v[76:79]
	v_mfma_f32_16x16x32_bf16 v[128:131], v[136:139], v[196:199], v[128:131]
	v_mfma_f32_16x16x32_bf16 v[124:127], v[144:147], v[196:199], v[124:127]
	v_mfma_f32_16x16x32_bf16 v[112:115], v[136:139], v[212:215], v[112:115]
	v_mfma_f32_16x16x32_bf16 v[108:111], v[144:147], v[212:215], v[108:111]
	v_mfma_f32_16x16x32_bf16 v[96:99], v[136:139], v[220:223], v[96:99]
	v_mfma_f32_16x16x32_bf16 v[92:95], v[144:147], v[220:223], v[92:95]
	v_mfma_f32_16x16x32_bf16 v[80:83], v[136:139], v[228:231], v[80:83]
	v_mfma_f32_16x16x32_bf16 v[76:79], v[144:147], v[228:231], v[76:79]
	v_mfma_f32_16x16x32_bf16 v[120:123], v[148:151], v[188:191], v[120:123]
	v_mfma_f32_16x16x32_bf16 v[116:119], v[180:183], v[188:191], v[116:119]
	v_mfma_f32_16x16x32_bf16 v[104:107], v[148:151], v[200:203], v[104:107]
	v_mfma_f32_16x16x32_bf16 v[100:103], v[180:183], v[200:203], v[100:103]
	v_mfma_f32_16x16x32_bf16 v[88:91], v[148:151], v[216:219], v[88:91]
	v_mfma_f32_16x16x32_bf16 v[84:87], v[180:183], v[216:219], v[84:87]
	v_mfma_f32_16x16x32_bf16 v[72:75], v[148:151], v[224:227], v[72:75]
	v_mfma_f32_16x16x32_bf16 v[68:71], v[180:183], v[224:227], v[68:71]
	v_mfma_f32_16x16x32_bf16 v[120:123], v[152:155], v[196:199], v[120:123]
	v_mfma_f32_16x16x32_bf16 v[116:119], v[184:187], v[196:199], v[116:119]
	v_mfma_f32_16x16x32_bf16 v[104:107], v[152:155], v[212:215], v[104:107]
	v_mfma_f32_16x16x32_bf16 v[100:103], v[184:187], v[212:215], v[100:103]
	v_mfma_f32_16x16x32_bf16 v[88:91], v[152:155], v[220:223], v[88:91]
	v_mfma_f32_16x16x32_bf16 v[84:87], v[184:187], v[220:223], v[84:87]
	v_mfma_f32_16x16x32_bf16 v[72:75], v[152:155], v[228:231], v[72:75]
	v_mfma_f32_16x16x32_bf16 v[68:71], v[184:187], v[228:231], v[68:71]
	s_barrier
	s_add_i32 s67, s67, s50
	s_add_u32 s98, s2, 0x80
	s_addc_u32 s99, s3, 0
	s_mov_b32 m0, s67
	ds_read_b128 v[188:191], v195 offset:16384
	ds_read_b128 v[196:199], v195 offset:17408
	ds_read_b128 v[200:203], v195 offset:18432
	ds_read_b128 v[212:215], v195 offset:19456
	ds_read_b128 v[216:219], v195 offset:20480
	ds_read_b128 v[220:223], v195 offset:21504
	ds_read_b128 v[224:227], v195 offset:22528
	ds_read_b128 v[228:231], v195 offset:23552
	global_load_lds_dwordx4 v172, s[2:3]
	s_add_i32 m0, s67, 0x2000
	s_add_u32 s68, s2, 0x80000
	s_addc_u32 s69, s3, 0
	s_add_i32 s67, s70, s50
	global_load_lds_dwordx4 v156, s[2:3]
	s_mov_b32 m0, s67
	s_add_u32 s100, s48, 0x80
	s_addc_u32 s101, s49, 0
	s_nop 0
	global_load_lds_dwordx4 v172, s[68:69]
	s_add_i32 m0, s67, 0x2000
	s_nop 0
	global_load_lds_dwordx4 v156, s[68:69]
	s_mov_b32 m0, s51
	s_nop 0
	global_load_lds_dwordx4 v174, s[48:49]
	s_mov_b32 m0, s54
	s_nop 0
	global_load_lds_dwordx4 v158, s[48:49]
	s_waitcnt vmcnt(8)
	s_waitcnt lgkmcnt(0)
	s_barrier
; #define PG8_STAGE(bufoff, gbase, voff) do { _Pragma("unroll") for (int _i = 0; _i < 2; ++_i) \
;         __builtin_amdgcn_global_load_lds((const unsigned*)((const char*)(gbase) + (voff)[_i]), (PG8_LAS unsigned*)(lds + (bufoff) + ldsw + _i * 8192), 16, 0, 0); } while (0)
; #define PG8_LDA(dst, b, h) do { _Pragma("unroll") for (int m = 0; m < 4; ++m) _Pragma("unroll") for (int k = 0; k < 2; ++k) dst[m][k] = *(const PG8_LAS bf16x8*)(lds + PG8_SA(b, h) + aoff + m * 2048 + k * 1024); } while (0)
; #define PG8_LDB(dst, b, h) do { _Pragma("unroll") for (int n = 0; n < 2; ++n) _Pragma("unroll") for (int k = 0; k < 2; ++k) dst[n][k] = *(const PG8_LAS bf16x8*)(lds + PG8_SB(b, h) + boff + n * 2048 + k * 1024); } while (0)
; #define PG8_MMA(ai, bj, At, Bt) do { __builtin_amdgcn_s_setprio(1); _Pragma("unroll") for (int m = 0; m < 4; ++m) _Pragma("unroll") for (int n = 0; n < 2; ++n) _Pragma("unroll") for (int k = 0; k < 2; ++k) \
;         acc[ai][bj][m][n] = __builtin_amdgcn_mfma_f32_16x16x32_bf16(Bt[n][k], At[m][k], acc[ai][bj][m][n], 0, 0, 0); __builtin_amdgcn_s_setprio(0); } while (0)
; #define PG8_WAIT_V(n) asm volatile("s_waitcnt vmcnt(" #n ")" ::: "memory")
; #define PG8_WAIT_L(n) asm volatile("s_waitcnt lgkmcnt(" #n ")" ::: "memory")
; #define PG8_BAR __builtin_amdgcn_s_barrier()
; #define PG8_SCHED __builtin_amdgcn_sched_barrier(0)
; template <class Epi, class Sched, bool ALIGN_EPI = false, bool SP2 = false>
; __device__ __forceinline__ void gemm_phase(PG8_LAS unsigned char* lds, const Gemm g, const Sched& S, const Epi& E) {
;     ...
;             PG8_WAIT_V(8); PG8_WAIT_L(0); PG8_BAR; PG8_MMA(1, 0, At, B0); PG8_MMA(1, 1, At, B1); PG8_BAR; PG8_SCHED;
;             PG8_LDB(B0, 1, 0); PG8_LDB(B1, 1, 1); PG8_SCHED; PG8_LDA(At, 1, 0); PG8_STAGE(PG8_SA(0, 1), a2 + hstep, voffA);
;             PG8_WAIT_V(8); PG8_WAIT_L(0); PG8_BAR; PG8_MMA(0, 0, At, B0); PG8_MMA(0, 1, At, B1); PG8_BAR; PG8_SCHED;
;             PG8_LDA(At, 1, 1); PG8_STAGE(PG8_SB(1, 0), b3, voffB); PG8_STAGE(PG8_SB(1, 1), b3 + hstep, voffB); PG8_STAGE(PG8_SA(1, 0), a3, voffA);
	s_waitcnt lgkmcnt(0)
	v_mfma_f32_16x16x32_bf16 v[64:67], v[132:135], v[188:191], v[64:67]
	v_mfma_f32_16x16x32_bf16 v[60:63], v[140:143], v[188:191], v[60:63]
	v_mfma_f32_16x16x32_bf16 v[48:51], v[132:135], v[200:203], v[48:51]
	v_mfma_f32_16x16x32_bf16 v[44:47], v[140:143], v[200:203], v[44:47]
	v_mfma_f32_16x16x32_bf16 v[32:35], v[132:135], v[216:219], v[32:35]
	v_mfma_f32_16x16x32_bf16 v[28:31], v[140:143], v[216:219], v[28:31]
	v_mfma_f32_16x16x32_bf16 v[16:19], v[132:135], v[224:227], v[16:19]
	v_mfma_f32_16x16x32_bf16 v[12:15], v[140:143], v[224:227], v[12:15]
	v_mfma_f32_16x16x32_bf16 v[64:67], v[136:139], v[196:199], v[64:67]
	v_mfma_f32_16x16x32_bf16 v[60:63], v[144:147], v[196:199], v[60:63]
	v_mfma_f32_16x16x32_bf16 v[48:51], v[136:139], v[212:215], v[48:51]
	v_mfma_f32_16x16x32_bf16 v[44:47], v[144:147], v[212:215], v[44:47]
	v_mfma_f32_16x16x32_bf16 v[32:35], v[136:139], v[220:223], v[32:35]
	v_mfma_f32_16x16x32_bf16 v[28:31], v[144:147], v[220:223], v[28:31]
	v_mfma_f32_16x16x32_bf16 v[16:19], v[136:139], v[228:231], v[16:19]
	v_mfma_f32_16x16x32_bf16 v[12:15], v[144:147], v[228:231], v[12:15]
	v_mfma_f32_16x16x32_bf16 v[56:59], v[148:151], v[188:191], v[56:59]
	v_mfma_f32_16x16x32_bf16 v[52:55], v[180:183], v[188:191], v[52:55]
	v_mfma_f32_16x16x32_bf16 v[40:43], v[148:151], v[200:203], v[40:43]
	v_mfma_f32_16x16x32_bf16 v[36:39], v[180:183], v[200:203], v[36:39]
	v_mfma_f32_16x16x32_bf16 v[24:27], v[148:151], v[216:219], v[24:27]
	v_mfma_f32_16x16x32_bf16 v[20:23], v[180:183], v[216:219], v[20:23]
	v_mfma_f32_16x16x32_bf16 v[8:11], v[148:151], v[224:227], v[8:11]
	v_mfma_f32_16x16x32_bf16 v[4:7], v[180:183], v[224:227], v[4:7]
	v_mfma_f32_16x16x32_bf16 v[56:59], v[152:155], v[196:199], v[56:59]
	v_mfma_f32_16x16x32_bf16 v[52:55], v[184:187], v[196:199], v[52:55]
	v_mfma_f32_16x16x32_bf16 v[40:43], v[152:155], v[212:215], v[40:43]
	v_mfma_f32_16x16x32_bf16 v[36:39], v[184:187], v[212:215], v[36:39]
	v_mfma_f32_16x16x32_bf16 v[24:27], v[152:155], v[220:223], v[24:27]
	v_mfma_f32_16x16x32_bf16 v[20:23], v[184:187], v[220:223], v[20:23]
	v_mfma_f32_16x16x32_bf16 v[8:11], v[152:155], v[228:231], v[8:11]
	v_mfma_f32_16x16x32_bf16 v[4:7], v[184:187], v[228:231], v[4:7]
	s_barrier
	s_add_i32 s67, 0, 0x18000
	s_add_i32 s68, 0, 0x1c000
	ds_read_b128 v[132:135], v170
	ds_read_b128 v[136:139], v170 offset:1024
	ds_read_b128 v[140:143], v170 offset:2048
	ds_read_b128 v[144:147], v170 offset:3072
	ds_read_b128 v[148:151], v171
	ds_read_b128 v[152:155], v171 offset:1024
	ds_read_b128 v[180:183], v171 offset:2048
	ds_read_b128 v[184:187], v171 offset:3072
	s_add_u32 s48, s48, 0x80000
	s_addc_u32 s49, s49, 0
	s_mov_b32 m0, s55
	ds_read_b128 v[188:191], v195 offset:32768
	ds_read_b128 v[196:199], v195 offset:33792
	ds_read_b128 v[200:203], v195 offset:34816
	ds_read_b128 v[212:215], v195 offset:35840
	ds_read_b128 v[216:219], v195 offset:36864
	ds_read_b128 v[220:223], v195 offset:37888
	ds_read_b128 v[224:227], v195 offset:38912
	ds_read_b128 v[228:231], v195 offset:39936
	global_load_lds_dwordx4 v174, s[48:49]
	s_mov_b32 m0, s56
	s_nop 0
	global_load_lds_dwordx4 v158, s[48:49]
	s_waitcnt vmcnt(8)
	s_waitcnt lgkmcnt(0)
	s_barrier
	s_waitcnt lgkmcnt(0)
	v_mfma_f32_16x16x32_bf16 v[128:131], v[132:135], v[188:191], v[128:131]
	v_mfma_f32_16x16x32_bf16 v[124:127], v[140:143], v[188:191], v[124:127]
	v_mfma_f32_16x16x32_bf16 v[112:115], v[132:135], v[200:203], v[112:115]
	v_mfma_f32_16x16x32_bf16 v[108:111], v[140:143], v[200:203], v[108:111]
	v_mfma_f32_16x16x32_bf16 v[96:99], v[132:135], v[216:219], v[96:99]
	v_mfma_f32_16x16x32_bf16 v[92:95], v[140:143], v[216:219], v[92:95]
	v_mfma_f32_16x16x32_bf16 v[80:83], v[132:135], v[224:227], v[80:83]
	v_mfma_f32_16x16x32_bf16 v[76:79], v[140:143], v[224:227], v[76:79]
	v_mfma_f32_16x16x32_bf16 v[128:131], v[136:139], v[196:199], v[128:131]
	v_mfma_f32_16x16x32_bf16 v[124:127], v[144:147], v[196:199], v[124:127]
	v_mfma_f32_16x16x32_bf16 v[112:115], v[136:139], v[212:215], v[112:115]
	v_mfma_f32_16x16x32_bf16 v[108:111], v[144:147], v[212:215], v[108:111]
	v_mfma_f32_16x16x32_bf16 v[96:99], v[136:139], v[220:223], v[96:99]
	v_mfma_f32_16x16x32_bf16 v[92:95], v[144:147], v[220:223], v[92:95]
	v_mfma_f32_16x16x32_bf16 v[80:83], v[136:139], v[228:231], v[80:83]
	v_mfma_f32_16x16x32_bf16 v[76:79], v[144:147], v[228:231], v[76:79]
	v_mfma_f32_16x16x32_bf16 v[120:123], v[148:151], v[188:191], v[120:123]
	v_mfma_f32_16x16x32_bf16 v[116:119], v[180:183], v[188:191], v[116:119]
	v_mfma_f32_16x16x32_bf16 v[104:107], v[148:151], v[200:203], v[104:107]
	v_mfma_f32_16x16x32_bf16 v[100:103], v[180:183], v[200:203], v[100:103]
	v_mfma_f32_16x16x32_bf16 v[88:91], v[148:151], v[216:219], v[88:91]
	v_mfma_f32_16x16x32_bf16 v[84:87], v[180:183], v[216:219], v[84:87]
	v_mfma_f32_16x16x32_bf16 v[72:75], v[148:151], v[224:227], v[72:75]
	v_mfma_f32_16x16x32_bf16 v[68:71], v[180:183], v[224:227], v[68:71]
	v_mfma_f32_16x16x32_bf16 v[120:123], v[152:155], v[196:199], v[120:123]
	v_mfma_f32_16x16x32_bf16 v[116:119], v[184:187], v[196:199], v[116:119]
	v_mfma_f32_16x16x32_bf16 v[104:107], v[152:155], v[212:215], v[104:107]
	v_mfma_f32_16x16x32_bf16 v[100:103], v[184:187], v[212:215], v[100:103]
	v_mfma_f32_16x16x32_bf16 v[88:91], v[152:155], v[220:223], v[88:91]
	v_mfma_f32_16x16x32_bf16 v[84:87], v[184:187], v[220:223], v[84:87]
	v_mfma_f32_16x16x32_bf16 v[72:75], v[152:155], v[228:231], v[72:75]
	v_mfma_f32_16x16x32_bf16 v[68:71], v[184:187], v[228:231], v[68:71]
	s_barrier
; #define PG8_STAGE(bufoff, gbase, voff) do { _Pragma("unroll") for (int _i = 0; _i < 2; ++_i) \
;         __builtin_amdgcn_global_load_lds((const unsigned*)((const char*)(gbase) + (voff)[_i]), (PG8_LAS unsigned*)(lds + (bufoff) + ldsw + _i * 8192), 16, 0, 0); } while (0)
; #define PG8_LDA(dst, b, h) do { _Pragma("unroll") for (int m = 0; m < 4; ++m) _Pragma("unroll") for (int k = 0; k < 2; ++k) dst[m][k] = *(const PG8_LAS bf16x8*)(lds + PG8_SA(b, h) + aoff + m * 2048 + k * 1024); } while (0)
; #define PG8_MMA(ai, bj, At, Bt) do { __builtin_amdgcn_s_setprio(1); _Pragma("unroll") for (int m = 0; m < 4; ++m) _Pragma("unroll") for (int n = 0; n < 2; ++n) _Pragma("unroll") for (int k = 0; k < 2; ++k) \
;         acc[ai][bj][m][n] = __builtin_amdgcn_mfma_f32_16x16x32_bf16(Bt[n][k], At[m][k], acc[ai][bj][m][n], 0, 0, 0); __builtin_amdgcn_s_setprio(0); } while (0)
; #define PG8_WAIT_V(n) asm volatile("s_waitcnt vmcnt(" #n ")" ::: "memory")
; #define PG8_WAIT_L(n) asm volatile("s_waitcnt lgkmcnt(" #n ")" ::: "memory")
; #define PG8_BAR __builtin_amdgcn_s_barrier()
; #define PG8_SCHED __builtin_amdgcn_sched_barrier(0)
; template <class Epi, class Sched, bool ALIGN_EPI = false, bool SP2 = false>
; __device__ __forceinline__ void gemm_phase(PG8_LAS unsigned char* lds, const Gemm g, const Sched& S, const Epi& E) {
;     ...
;             PG8_LDA(At, 1, 1); PG8_STAGE(PG8_SB(1, 0), b3, voffB); PG8_STAGE(PG8_SB(1, 1), b3 + hstep, voffB); PG8_STAGE(PG8_SA(1, 0), a3, voffA);
;             PG8_WAIT_V(8); PG8_WAIT_L(0); PG8_BAR; PG8_MMA(1, 0, At, B0); PG8_MMA(1, 1, At, B1); PG8_BAR; PG8_SCHED;
	s_add_i32 s48, s67, s50
	s_mov_b32 m0, s48
	ds_read_b128 v[188:191], v195 offset:49152
	ds_read_b128 v[196:199], v195 offset:50176
	ds_read_b128 v[200:203], v195 offset:51200
	ds_read_b128 v[212:215], v195 offset:52224
	ds_read_b128 v[216:219], v195 offset:53248
	ds_read_b128 v[220:223], v195 offset:54272
	ds_read_b128 v[224:227], v195 offset:55296
	ds_read_b128 v[228:231], v195 offset:56320
	global_load_lds_dwordx4 v172, s[98:99]
	s_add_i32 m0, s48, 0x2000
	s_add_u32 s2, s2, 0x80080
	s_addc_u32 s3, s3, 0
	s_add_i32 s48, s68, s50
	global_load_lds_dwordx4 v156, s[98:99]
	s_mov_b32 m0, s48
	s_nop 0
	global_load_lds_dwordx4 v172, s[2:3]
	s_add_i32 m0, s48, 0x2000
	s_nop 0
	global_load_lds_dwordx4 v156, s[2:3]
	s_mov_b32 m0, s57
	s_nop 0
	global_load_lds_dwordx4 v174, s[100:101]
	s_mov_b32 m0, s58
	s_nop 0
	global_load_lds_dwordx4 v158, s[100:101]
	s_waitcnt vmcnt(8)
	s_waitcnt lgkmcnt(0)
	s_barrier
	s_waitcnt lgkmcnt(0)
	v_mfma_f32_16x16x32_bf16 v[64:67], v[132:135], v[188:191], v[64:67]
	v_mfma_f32_16x16x32_bf16 v[60:63], v[140:143], v[188:191], v[60:63]
	v_mfma_f32_16x16x32_bf16 v[48:51], v[132:135], v[200:203], v[48:51]
	v_mfma_f32_16x16x32_bf16 v[44:47], v[140:143], v[200:203], v[44:47]
	v_mfma_f32_16x16x32_bf16 v[32:35], v[132:135], v[216:219], v[32:35]
	v_mfma_f32_16x16x32_bf16 v[28:31], v[140:143], v[216:219], v[28:31]
	v_mfma_f32_16x16x32_bf16 v[16:19], v[132:135], v[224:227], v[16:19]
	v_mfma_f32_16x16x32_bf16 v[12:15], v[140:143], v[224:227], v[12:15]
	v_mfma_f32_16x16x32_bf16 v[64:67], v[136:139], v[196:199], v[64:67]
	v_mfma_f32_16x16x32_bf16 v[60:63], v[144:147], v[196:199], v[60:63]
	v_mfma_f32_16x16x32_bf16 v[48:51], v[136:139], v[212:215], v[48:51]
	v_mfma_f32_16x16x32_bf16 v[44:47], v[144:147], v[212:215], v[44:47]
	v_mfma_f32_16x16x32_bf16 v[32:35], v[136:139], v[220:223], v[32:35]
	v_mfma_f32_16x16x32_bf16 v[28:31], v[144:147], v[220:223], v[28:31]
	v_mfma_f32_16x16x32_bf16 v[16:19], v[136:139], v[228:231], v[16:19]
	v_mfma_f32_16x16x32_bf16 v[12:15], v[144:147], v[228:231], v[12:15]
	v_mfma_f32_16x16x32_bf16 v[56:59], v[148:151], v[188:191], v[56:59]
	v_mfma_f32_16x16x32_bf16 v[52:55], v[180:183], v[188:191], v[52:55]
	v_mfma_f32_16x16x32_bf16 v[40:43], v[148:151], v[200:203], v[40:43]
	v_mfma_f32_16x16x32_bf16 v[36:39], v[180:183], v[200:203], v[36:39]
	v_mfma_f32_16x16x32_bf16 v[24:27], v[148:151], v[216:219], v[24:27]
	v_mfma_f32_16x16x32_bf16 v[20:23], v[180:183], v[216:219], v[20:23]
	v_mfma_f32_16x16x32_bf16 v[8:11], v[148:151], v[224:227], v[8:11]
	v_mfma_f32_16x16x32_bf16 v[4:7], v[180:183], v[224:227], v[4:7]
	v_mfma_f32_16x16x32_bf16 v[56:59], v[152:155], v[196:199], v[56:59]
	v_mfma_f32_16x16x32_bf16 v[52:55], v[184:187], v[196:199], v[52:55]
	v_mfma_f32_16x16x32_bf16 v[40:43], v[152:155], v[212:215], v[40:43]
	v_mfma_f32_16x16x32_bf16 v[36:39], v[184:187], v[212:215], v[36:39]
	v_mfma_f32_16x16x32_bf16 v[24:27], v[152:155], v[220:223], v[24:27]
	v_mfma_f32_16x16x32_bf16 v[20:23], v[184:187], v[220:223], v[20:23]
	v_mfma_f32_16x16x32_bf16 v[8:11], v[152:155], v[228:231], v[8:11]
	v_mfma_f32_16x16x32_bf16 v[4:7], v[184:187], v[228:231], v[4:7]
	s_barrier
	s_add_i32 s66, s66, 2
	s_add_u32 s46, s46, 0x100
	s_addc_u32 s47, s47, 0
	s_cmp_gt_u32 s66, 29
	s_cbranch_scc1 .LBB0_929

; #define PG8_BAR __builtin_amdgcn_s_barrier()
; template <class Epi, class Sched, bool ALIGN_EPI = false, bool SP2 = false>
; __device__ __forceinline__ void gemm_phase(PG8_LAS unsigned char* lds, const Gemm g, const Sched& S, const Epi& E) {
;     ...
;         if constexpr (ALIGN_EPI) { if (wr == 0) PG8_BAR; }
;         if constexpr (!Epi::AFTER_DRAIN) { E(acc, cur, wr, wc, fr, fq); S.done(cur); }
.LBB0_929:
	s_setprio 0
	s_and_b64 vcc, exec, s[14:15]
	s_cbranch_vccz .LBB0_931
	s_barrier

; #define PG8_STAGE(bufoff, gbase, voff) do { _Pragma("unroll") for (int _i = 0; _i < 2; ++_i) \
;         __builtin_amdgcn_global_load_lds((const unsigned*)((const char*)(gbase) + (voff)[_i]), (PG8_LAS unsigned*)(lds + (bufoff) + ldsw + _i * 8192), 16, 0, 0); } while (0)
; #define PG8_LDA(dst, b, h) do { _Pragma("unroll") for (int m = 0; m < 4; ++m) _Pragma("unroll") for (int k = 0; k < 2; ++k) dst[m][k] = *(const PG8_LAS bf16x8*)(lds + PG8_SA(b, h) + aoff + m * 2048 + k * 1024); } while (0)
; #define PG8_LDB(dst, b, h) do { _Pragma("unroll") for (int n = 0; n < 2; ++n) _Pragma("unroll") for (int k = 0; k < 2; ++k) dst[n][k] = *(const PG8_LAS bf16x8*)(lds + PG8_SB(b, h) + boff + n * 2048 + k * 1024); } while (0)
; #define PG8_SCHED __builtin_amdgcn_sched_barrier(0)
; template <class Epi, class Sched, bool ALIGN_EPI = false, bool SP2 = false>
; __device__ __forceinline__ void gemm_phase(PG8_LAS unsigned char* lds, const Gemm g, const Sched& S, const Epi& E) {
;     ...
;         const bool has_next = S.next(ui + 1, nxt);
;         const char* nA = has_next ? (const char*)g.A + (size_t)nxt.pm * tstep : cA; const char* nB = has_next ? (const char*)g.Bt + (size_t)nxt.pn * tstep : cB;
;         for (int t = 0; t < nt; t += 2) {
;             const bool last = (t == nt - 2);
;             const char* a1 = cA + (size_t)(t + 1) * kstep;
;             const char* a2 = last ? nA : cA + (size_t)(t + 2) * kstep; const char* b2 = last ? nB : cB + (size_t)(t + 2) * kstep;
;             const char* a3 = a2 + kstep; const char* b3 = b2 + kstep;
;             if (last && has_next) S.a_ready(nxt);
;             if constexpr (Epi::KSPLIT) { if (t == (nt >> 1)) E.mid(acc, cur, wr, wc, fr, fq); }
;             if constexpr (SP2) {
;             PG8_LDB(B0, 0, 0); PG8_LDB(B1, 0, 1); PG8_SCHED; PG8_LDA(At, 0, 0); PG8_STAGE(PG8_SA(1, 1), a1 + hstep, voffA);
;     ...
;         for (int a = 0; a < 2; ++a)
; #pragma unroll
;             for (int b = 0; b < 2; ++b)
; #pragma unroll
;                 for (int m = 0; m < 4; ++m)
; #pragma unroll
;                     for (int n = 0; n < 2; ++n) acc[a][b][m][n] = (f32x4){0.f, 0.f, 0.f, 0.f};
;         cur = nxt; cA = nA; cB = nB; ++ui;
.LBB0_1050:
	s_mov_b64 s[2:3], s[6:7]
	s_mov_b32 s6, s51
	s_add_i32 s51, s51, 1
	s_sub_i32 s7, 3, s6
	s_cmp_lt_u32 s6, 4
	s_cselect_b32 s6, s7, s51
	s_mov_b32 s52, s12
	s_lshl_b32 s6, s6, 3
	v_readlane_b32 s12, v248, 25
	s_add_i32 s12, s6, s12
	v_readlane_b32 s13, v248, 26
	s_cmp_lt_i32 s12, 44
	s_cselect_b64 s[14:15], -1, 0
	s_ashr_i32 s13, s12, 31
	s_lshl_b64 s[6:7], s[12:13], 20
	s_add_u32 s6, s46, s6
	s_addc_u32 s7, s47, s7
	s_and_b64 s[36:37], s[14:15], exec
	s_cselect_b32 s13, s7, s3
	s_cselect_b32 s53, s6, s2
	s_add_u32 s54, s2, 0x100
	v_mov_b32_e32 v12, 0
	s_addc_u32 s55, s3, 0
	s_mov_b32 s56, -2
	s_mov_b64 s[2:3], 0
	v_mov_b32_e32 v13, v12
	v_mov_b32_e32 v14, v12
	v_mov_b32_e32 v15, v12
	v_mov_b32_e32 v16, v12
	v_mov_b32_e32 v17, v12
	v_mov_b32_e32 v18, v12
	v_mov_b32_e32 v19, v12
	v_mov_b32_e32 v28, v12
	v_mov_b32_e32 v29, v12
	v_mov_b32_e32 v30, v12
	v_mov_b32_e32 v31, v12
	v_mov_b32_e32 v32, v12
	v_mov_b32_e32 v33, v12
	v_mov_b32_e32 v34, v12
	v_mov_b32_e32 v35, v12
	v_mov_b32_e32 v44, v12
	v_mov_b32_e32 v45, v12
	v_mov_b32_e32 v46, v12
	v_mov_b32_e32 v47, v12
	v_mov_b32_e32 v48, v12
	v_mov_b32_e32 v49, v12
	v_mov_b32_e32 v50, v12
	v_mov_b32_e32 v51, v12
	v_mov_b32_e32 v60, v12
	v_mov_b32_e32 v61, v12
	v_mov_b32_e32 v62, v12
	v_mov_b32_e32 v63, v12
	v_mov_b32_e32 v64, v12
	v_mov_b32_e32 v65, v12
	v_mov_b32_e32 v66, v12
	v_mov_b32_e32 v67, v12
	v_mov_b32_e32 v4, v12
	v_mov_b32_e32 v5, v12
	v_mov_b32_e32 v6, v12
	v_mov_b32_e32 v7, v12
	v_mov_b32_e32 v8, v12
	v_mov_b32_e32 v9, v12
	v_mov_b32_e32 v10, v12
	v_mov_b32_e32 v11, v12
	v_mov_b32_e32 v20, v12
	v_mov_b32_e32 v21, v12
	v_mov_b32_e32 v22, v12
	v_mov_b32_e32 v23, v12
	v_mov_b32_e32 v24, v12
	v_mov_b32_e32 v25, v12
	v_mov_b32_e32 v26, v12
	v_mov_b32_e32 v27, v12
	v_mov_b32_e32 v36, v12
	v_mov_b32_e32 v37, v12
	v_mov_b32_e32 v38, v12
	v_mov_b32_e32 v39, v12
	v_mov_b32_e32 v40, v12
	v_mov_b32_e32 v41, v12
	v_mov_b32_e32 v42, v12
	v_mov_b32_e32 v43, v12
	v_mov_b32_e32 v52, v12
	v_mov_b32_e32 v53, v12
	v_mov_b32_e32 v54, v12
	v_mov_b32_e32 v55, v12
	v_mov_b32_e32 v56, v12
	v_mov_b32_e32 v57, v12
	v_mov_b32_e32 v58, v12
	v_mov_b32_e32 v59, v12
	v_mov_b32_e32 v76, v12
	v_mov_b32_e32 v77, v12
	v_mov_b32_e32 v78, v12
	v_mov_b32_e32 v79, v12
	v_mov_b32_e32 v80, v12
	v_mov_b32_e32 v81, v12
	v_mov_b32_e32 v82, v12
	v_mov_b32_e32 v83, v12
	v_mov_b32_e32 v92, v12
	v_mov_b32_e32 v93, v12
	v_mov_b32_e32 v94, v12
	v_mov_b32_e32 v95, v12
	v_mov_b32_e32 v96, v12
	v_mov_b32_e32 v97, v12
	v_mov_b32_e32 v98, v12
	v_mov_b32_e32 v99, v12
	v_mov_b32_e32 v108, v12
	v_mov_b32_e32 v109, v12
	v_mov_b32_e32 v110, v12
	v_mov_b32_e32 v111, v12
	v_mov_b32_e32 v112, v12
	v_mov_b32_e32 v113, v12
	v_mov_b32_e32 v114, v12
	v_mov_b32_e32 v115, v12
	v_mov_b32_e32 v124, v12
	v_mov_b32_e32 v125, v12
	v_mov_b32_e32 v126, v12
	v_mov_b32_e32 v127, v12
	v_mov_b32_e32 v128, v12
	v_mov_b32_e32 v129, v12
	v_mov_b32_e32 v130, v12
	v_mov_b32_e32 v131, v12
	v_mov_b32_e32 v68, v12
	v_mov_b32_e32 v69, v12
	v_mov_b32_e32 v70, v12
	v_mov_b32_e32 v71, v12
	v_mov_b32_e32 v72, v12
	v_mov_b32_e32 v73, v12
	v_mov_b32_e32 v74, v12
	v_mov_b32_e32 v75, v12
	v_mov_b32_e32 v84, v12
	v_mov_b32_e32 v85, v12
	v_mov_b32_e32 v86, v12
	v_mov_b32_e32 v87, v12
	v_mov_b32_e32 v88, v12
	v_mov_b32_e32 v89, v12
	v_mov_b32_e32 v90, v12
	v_mov_b32_e32 v91, v12
	v_mov_b32_e32 v100, v12
	v_mov_b32_e32 v101, v12
	v_mov_b32_e32 v102, v12
	v_mov_b32_e32 v103, v12
	v_mov_b32_e32 v104, v12
	v_mov_b32_e32 v105, v12
	v_mov_b32_e32 v106, v12
	v_mov_b32_e32 v107, v12
	v_mov_b32_e32 v116, v12
	v_mov_b32_e32 v117, v12
	v_mov_b32_e32 v118, v12
	v_mov_b32_e32 v119, v12
	v_mov_b32_e32 v120, v12
	v_mov_b32_e32 v121, v12
	v_mov_b32_e32 v122, v12
	v_mov_b32_e32 v123, v12
	v_add_u32_e32 v168, 0x10000, v3
	v_add_u32_e32 v169, 0x14000, v3
	v_add_u32_e32 v170, 0x18000, v3
	v_add_u32_e32 v171, 0x1c000, v3
	s_cmp_lg_u64 s[10:11], 0
	s_cbranch_scc1 .Lprio_P4
	s_setprio 1
.Lprio_P4:
.LBB0_1051:
	s_add_u32 s36, s31, s2
	s_addc_u32 s37, s91, s3
	s_add_u32 s36, s36, 0x16200100
	s_addc_u32 s37, s37, 0
	s_add_u32 s57, s54, s2
	s_addc_u32 s58, s55, s3
	s_add_i32 s59, 0, 0x10000
	s_cmpk_eq_i32 s2, 0xf00
	s_cselect_b32 s41, s1, s37
	s_cselect_b32 s40, s0, s36
	s_cselect_b32 s37, s13, s58
	s_cselect_b32 s36, s53, s57
	s_add_i32 s57, 0, 0x14000
	ds_read_b128 v[142:145], v168
	ds_read_b128 v[152:155], v168 offset:1024
	ds_read_b128 v[156:159], v168 offset:2048
	ds_read_b128 v[172:175], v168 offset:3072
	ds_read_b128 v[176:179], v169
	ds_read_b128 v[180:183], v169 offset:1024
	ds_read_b128 v[184:187], v169 offset:2048
	ds_read_b128 v[188:191], v169 offset:3072
	v_lshl_add_u64 v[146:147], v[138:139], 0, s[2:3]
	s_add_i32 m0, s43, 0xc000
	ds_read_b128 v[192:195], v150
	ds_read_b128 v[196:199], v150 offset:1024
	ds_read_b128 v[200:203], v150 offset:2048
	ds_read_b128 v[212:215], v150 offset:3072
	ds_read_b128 v[216:219], v150 offset:4096
	ds_read_b128 v[220:223], v150 offset:5120
	ds_read_b128 v[224:227], v150 offset:6144
	ds_read_b128 v[228:231], v150 offset:7168
	global_load_lds_dwordx4 v[146:147], off
	v_lshl_add_u64 v[146:147], v[140:141], 0, s[2:3]
	s_add_i32 m0, s43, 0xe000
	s_nop 0
	global_load_lds_dwordx4 v[146:147], off
	s_waitcnt vmcnt(8)
	s_waitcnt lgkmcnt(0)
	s_barrier
; #define PG8_STAGE(bufoff, gbase, voff) do { _Pragma("unroll") for (int _i = 0; _i < 2; ++_i) \
;         __builtin_amdgcn_global_load_lds((const unsigned*)((const char*)(gbase) + (voff)[_i]), (PG8_LAS unsigned*)(lds + (bufoff) + ldsw + _i * 8192), 16, 0, 0); } while (0)
; #define PG8_LDA(dst, b, h) do { _Pragma("unroll") for (int m = 0; m < 4; ++m) _Pragma("unroll") for (int k = 0; k < 2; ++k) dst[m][k] = *(const PG8_LAS bf16x8*)(lds + PG8_SA(b, h) + aoff + m * 2048 + k * 1024); } while (0)
; #define PG8_LDB(dst, b, h) do { _Pragma("unroll") for (int n = 0; n < 2; ++n) _Pragma("unroll") for (int k = 0; k < 2; ++k) dst[n][k] = *(const PG8_LAS bf16x8*)(lds + PG8_SB(b, h) + boff + n * 2048 + k * 1024); } while (0)
; #define PG8_MMA(ai, bj, At, Bt) do { __builtin_amdgcn_s_setprio(1); _Pragma("unroll") for (int m = 0; m < 4; ++m) _Pragma("unroll") for (int n = 0; n < 2; ++n) _Pragma("unroll") for (int k = 0; k < 2; ++k) \
;         acc[ai][bj][m][n] = __builtin_amdgcn_mfma_f32_16x16x32_bf16(Bt[n][k], At[m][k], acc[ai][bj][m][n], 0, 0, 0); __builtin_amdgcn_s_setprio(0); } while (0)
; #define PG8_WAIT_V(n) asm volatile("s_waitcnt vmcnt(" #n ")" ::: "memory")
; #define PG8_WAIT_L(n) asm volatile("s_waitcnt lgkmcnt(" #n ")" ::: "memory")
; #define PG8_BAR __builtin_amdgcn_s_barrier()
; #define PG8_SCHED __builtin_amdgcn_sched_barrier(0)
; template <class Epi, class Sched, bool ALIGN_EPI = false, bool SP2 = false>
; __device__ __forceinline__ void gemm_phase(PG8_LAS unsigned char* lds, const Gemm g, const Sched& S, const Epi& E) {
;     ...
;             PG8_LDB(B0, 0, 0); PG8_LDB(B1, 0, 1); PG8_SCHED; PG8_LDA(At, 0, 0); PG8_STAGE(PG8_SA(1, 1), a1 + hstep, voffA);
;             PG8_WAIT_V(8); PG8_WAIT_L(0); PG8_BAR; PG8_MMA(0, 0, At, B0); PG8_MMA(0, 1, At, B1); PG8_BAR; PG8_SCHED;
;             PG8_LDA(At, 0, 1); PG8_STAGE(PG8_SB(0, 0), b2, voffB); PG8_STAGE(PG8_SB(0, 1), b2 + hstep, voffB); PG8_STAGE(PG8_SA(0, 0), a2, voffA);
;             PG8_WAIT_V(8); PG8_WAIT_L(0); PG8_BAR; PG8_MMA(1, 0, At, B0); PG8_MMA(1, 1, At, B1); PG8_BAR; PG8_SCHED;
	s_waitcnt lgkmcnt(0)
	v_mfma_f32_16x16x32_bf16 v[120:123], v[142:145], v[192:195], v[120:123]
	v_mfma_f32_16x16x32_bf16 v[116:119], v[156:159], v[192:195], v[116:119]
	v_mfma_f32_16x16x32_bf16 v[104:107], v[142:145], v[200:203], v[104:107]
	v_mfma_f32_16x16x32_bf16 v[100:103], v[156:159], v[200:203], v[100:103]
	v_mfma_f32_16x16x32_bf16 v[88:91], v[142:145], v[216:219], v[88:91]
	v_mfma_f32_16x16x32_bf16 v[84:87], v[156:159], v[216:219], v[84:87]
	v_mfma_f32_16x16x32_bf16 v[72:75], v[142:145], v[224:227], v[72:75]
	v_mfma_f32_16x16x32_bf16 v[68:71], v[156:159], v[224:227], v[68:71]
	v_mfma_f32_16x16x32_bf16 v[120:123], v[152:155], v[196:199], v[120:123]
	v_mfma_f32_16x16x32_bf16 v[116:119], v[172:175], v[196:199], v[116:119]
	v_mfma_f32_16x16x32_bf16 v[104:107], v[152:155], v[212:215], v[104:107]
	v_mfma_f32_16x16x32_bf16 v[100:103], v[172:175], v[212:215], v[100:103]
	v_mfma_f32_16x16x32_bf16 v[88:91], v[152:155], v[220:223], v[88:91]
	v_mfma_f32_16x16x32_bf16 v[84:87], v[172:175], v[220:223], v[84:87]
	v_mfma_f32_16x16x32_bf16 v[72:75], v[152:155], v[228:231], v[72:75]
	v_mfma_f32_16x16x32_bf16 v[68:71], v[172:175], v[228:231], v[68:71]
	v_mfma_f32_16x16x32_bf16 v[128:131], v[176:179], v[192:195], v[128:131]
	v_mfma_f32_16x16x32_bf16 v[124:127], v[184:187], v[192:195], v[124:127]
	v_mfma_f32_16x16x32_bf16 v[112:115], v[176:179], v[200:203], v[112:115]
	v_mfma_f32_16x16x32_bf16 v[108:111], v[184:187], v[200:203], v[108:111]
	v_mfma_f32_16x16x32_bf16 v[96:99], v[176:179], v[216:219], v[96:99]
	v_mfma_f32_16x16x32_bf16 v[92:95], v[184:187], v[216:219], v[92:95]
	v_mfma_f32_16x16x32_bf16 v[80:83], v[176:179], v[224:227], v[80:83]
	v_mfma_f32_16x16x32_bf16 v[76:79], v[184:187], v[224:227], v[76:79]
	v_mfma_f32_16x16x32_bf16 v[128:131], v[180:183], v[196:199], v[128:131]
	v_mfma_f32_16x16x32_bf16 v[124:127], v[188:191], v[196:199], v[124:127]
	v_mfma_f32_16x16x32_bf16 v[112:115], v[180:183], v[212:215], v[112:115]
	v_mfma_f32_16x16x32_bf16 v[108:111], v[188:191], v[212:215], v[108:111]
	v_mfma_f32_16x16x32_bf16 v[96:99], v[180:183], v[220:223], v[96:99]
	v_mfma_f32_16x16x32_bf16 v[92:95], v[188:191], v[220:223], v[92:95]
	v_mfma_f32_16x16x32_bf16 v[80:83], v[180:183], v[228:231], v[80:83]
	v_mfma_f32_16x16x32_bf16 v[76:79], v[188:191], v[228:231], v[76:79]
	s_barrier
	s_add_i32 s58, s59, s42
	s_add_u32 s98, s36, 0x80
	s_addc_u32 s99, s37, 0
	s_mov_b32 m0, s58
	ds_read_b128 v[192:195], v150 offset:16384
	ds_read_b128 v[196:199], v150 offset:17408
	ds_read_b128 v[200:203], v150 offset:18432
	ds_read_b128 v[212:215], v150 offset:19456
	ds_read_b128 v[216:219], v150 offset:20480
	ds_read_b128 v[220:223], v150 offset:21504
	ds_read_b128 v[224:227], v150 offset:22528
	ds_read_b128 v[228:231], v150 offset:23552
	global_load_lds_dwordx4 v134, s[36:37]
	s_add_i32 m0, s58, 0x2000
	s_add_u32 s58, s36, 0x80000
	s_addc_u32 s59, s37, 0
	s_add_i32 s57, s57, s42
	global_load_lds_dwordx4 v0, s[36:37]
	s_mov_b32 m0, s57
	s_add_u32 s100, s40, 0x80
	s_addc_u32 s101, s41, 0
	s_nop 0
	global_load_lds_dwordx4 v134, s[58:59]
	s_add_i32 m0, s57, 0x2000
	s_nop 0
	global_load_lds_dwordx4 v0, s[58:59]
	s_mov_b32 m0, s43
	s_nop 0
	global_load_lds_dwordx4 v136, s[40:41]
	s_mov_b32 m0, s44
	s_nop 0
	global_load_lds_dwordx4 v132, s[40:41]
	s_waitcnt vmcnt(8)
	s_waitcnt lgkmcnt(0)
	s_barrier
	s_waitcnt lgkmcnt(0)
	v_mfma_f32_16x16x32_bf16 v[56:59], v[142:145], v[192:195], v[56:59]
	v_mfma_f32_16x16x32_bf16 v[52:55], v[156:159], v[192:195], v[52:55]
	v_mfma_f32_16x16x32_bf16 v[40:43], v[142:145], v[200:203], v[40:43]
	v_mfma_f32_16x16x32_bf16 v[36:39], v[156:159], v[200:203], v[36:39]
	v_mfma_f32_16x16x32_bf16 v[24:27], v[142:145], v[216:219], v[24:27]
	v_mfma_f32_16x16x32_bf16 v[20:23], v[156:159], v[216:219], v[20:23]
	v_mfma_f32_16x16x32_bf16 v[8:11], v[142:145], v[224:227], v[8:11]
	v_mfma_f32_16x16x32_bf16 v[4:7], v[156:159], v[224:227], v[4:7]
	v_mfma_f32_16x16x32_bf16 v[56:59], v[152:155], v[196:199], v[56:59]
	v_mfma_f32_16x16x32_bf16 v[52:55], v[172:175], v[196:199], v[52:55]
	v_mfma_f32_16x16x32_bf16 v[40:43], v[152:155], v[212:215], v[40:43]
	v_mfma_f32_16x16x32_bf16 v[36:39], v[172:175], v[212:215], v[36:39]
	v_mfma_f32_16x16x32_bf16 v[24:27], v[152:155], v[220:223], v[24:27]
	v_mfma_f32_16x16x32_bf16 v[20:23], v[172:175], v[220:223], v[20:23]
	v_mfma_f32_16x16x32_bf16 v[8:11], v[152:155], v[228:231], v[8:11]
	v_mfma_f32_16x16x32_bf16 v[4:7], v[172:175], v[228:231], v[4:7]
	v_mfma_f32_16x16x32_bf16 v[64:67], v[176:179], v[192:195], v[64:67]
	v_mfma_f32_16x16x32_bf16 v[60:63], v[184:187], v[192:195], v[60:63]
	v_mfma_f32_16x16x32_bf16 v[48:51], v[176:179], v[200:203], v[48:51]
	v_mfma_f32_16x16x32_bf16 v[44:47], v[184:187], v[200:203], v[44:47]
	v_mfma_f32_16x16x32_bf16 v[32:35], v[176:179], v[216:219], v[32:35]
	v_mfma_f32_16x16x32_bf16 v[28:31], v[184:187], v[216:219], v[28:31]
	v_mfma_f32_16x16x32_bf16 v[16:19], v[176:179], v[224:227], v[16:19]
	v_mfma_f32_16x16x32_bf16 v[12:15], v[184:187], v[224:227], v[12:15]
	v_mfma_f32_16x16x32_bf16 v[64:67], v[180:183], v[196:199], v[64:67]
	v_mfma_f32_16x16x32_bf16 v[60:63], v[188:191], v[196:199], v[60:63]
	v_mfma_f32_16x16x32_bf16 v[48:51], v[180:183], v[212:215], v[48:51]
	v_mfma_f32_16x16x32_bf16 v[44:47], v[188:191], v[212:215], v[44:47]
	v_mfma_f32_16x16x32_bf16 v[32:35], v[180:183], v[220:223], v[32:35]
	v_mfma_f32_16x16x32_bf16 v[28:31], v[188:191], v[220:223], v[28:31]
	v_mfma_f32_16x16x32_bf16 v[16:19], v[180:183], v[228:231], v[16:19]
	v_mfma_f32_16x16x32_bf16 v[12:15], v[188:191], v[228:231], v[12:15]
	s_barrier
; #define PG8_STAGE(bufoff, gbase, voff) do { _Pragma("unroll") for (int _i = 0; _i < 2; ++_i) \
;         __builtin_amdgcn_global_load_lds((const unsigned*)((const char*)(gbase) + (voff)[_i]), (PG8_LAS unsigned*)(lds + (bufoff) + ldsw + _i * 8192), 16, 0, 0); } while (0)
; #define PG8_LDA(dst, b, h) do { _Pragma("unroll") for (int m = 0; m < 4; ++m) _Pragma("unroll") for (int k = 0; k < 2; ++k) dst[m][k] = *(const PG8_LAS bf16x8*)(lds + PG8_SA(b, h) + aoff + m * 2048 + k * 1024); } while (0)
; #define PG8_LDB(dst, b, h) do { _Pragma("unroll") for (int n = 0; n < 2; ++n) _Pragma("unroll") for (int k = 0; k < 2; ++k) dst[n][k] = *(const PG8_LAS bf16x8*)(lds + PG8_SB(b, h) + boff + n * 2048 + k * 1024); } while (0)
; #define PG8_MMA(ai, bj, At, Bt) do { __builtin_amdgcn_s_setprio(1); _Pragma("unroll") for (int m = 0; m < 4; ++m) _Pragma("unroll") for (int n = 0; n < 2; ++n) _Pragma("unroll") for (int k = 0; k < 2; ++k) \
;         acc[ai][bj][m][n] = __builtin_amdgcn_mfma_f32_16x16x32_bf16(Bt[n][k], At[m][k], acc[ai][bj][m][n], 0, 0, 0); __builtin_amdgcn_s_setprio(0); } while (0)
; #define PG8_WAIT_V(n) asm volatile("s_waitcnt vmcnt(" #n ")" ::: "memory")
; #define PG8_WAIT_L(n) asm volatile("s_waitcnt lgkmcnt(" #n ")" ::: "memory")
; #define PG8_BAR __builtin_amdgcn_s_barrier()
; #define PG8_SCHED __builtin_amdgcn_sched_barrier(0)
; template <class Epi, class Sched, bool ALIGN_EPI = false, bool SP2 = false>
; __device__ __forceinline__ void gemm_phase(PG8_LAS unsigned char* lds, const Gemm g, const Sched& S, const Epi& E) {
;     ...
;             PG8_LDB(B0, 1, 0); PG8_LDB(B1, 1, 1); PG8_SCHED; PG8_LDA(At, 1, 0); PG8_STAGE(PG8_SA(0, 1), a2 + hstep, voffA);
;             PG8_WAIT_V(8); PG8_WAIT_L(0); PG8_BAR; PG8_MMA(0, 0, At, B0); PG8_MMA(0, 1, At, B1); PG8_BAR; PG8_SCHED;
;             PG8_LDA(At, 1, 1); PG8_STAGE(PG8_SB(1, 0), b3, voffB); PG8_STAGE(PG8_SB(1, 1), b3 + hstep, voffB); PG8_STAGE(PG8_SA(1, 0), a3, voffA);
;             PG8_WAIT_V(8); PG8_WAIT_L(0); PG8_BAR; PG8_MMA(1, 0, At, B0); PG8_MMA(1, 1, At, B1); PG8_BAR; PG8_SCHED;
;     ...
;         if constexpr (ALIGN_EPI) { if (wr == 0) PG8_BAR; }
	s_add_i32 s57, 0, 0x18000
	s_add_i32 s58, 0, 0x1c000
	ds_read_b128 v[142:145], v170
	ds_read_b128 v[152:155], v170 offset:1024
	ds_read_b128 v[156:159], v170 offset:2048
	ds_read_b128 v[172:175], v170 offset:3072
	ds_read_b128 v[176:179], v171
	ds_read_b128 v[180:183], v171 offset:1024
	ds_read_b128 v[184:187], v171 offset:2048
	ds_read_b128 v[188:191], v171 offset:3072
	s_add_u32 s40, s40, 0x80000
	s_addc_u32 s41, s41, 0
	s_mov_b32 m0, s45
	ds_read_b128 v[192:195], v150 offset:32768
	ds_read_b128 v[196:199], v150 offset:33792
	ds_read_b128 v[200:203], v150 offset:34816
	ds_read_b128 v[212:215], v150 offset:35840
	ds_read_b128 v[216:219], v150 offset:36864
	ds_read_b128 v[220:223], v150 offset:37888
	ds_read_b128 v[224:227], v150 offset:38912
	ds_read_b128 v[228:231], v150 offset:39936
	global_load_lds_dwordx4 v136, s[40:41]
	s_mov_b32 m0, s48
	s_nop 0
	global_load_lds_dwordx4 v132, s[40:41]
	s_waitcnt vmcnt(8)
	s_waitcnt lgkmcnt(0)
	s_barrier
	s_waitcnt lgkmcnt(0)
	v_mfma_f32_16x16x32_bf16 v[120:123], v[142:145], v[192:195], v[120:123]
	v_mfma_f32_16x16x32_bf16 v[116:119], v[156:159], v[192:195], v[116:119]
	v_mfma_f32_16x16x32_bf16 v[104:107], v[142:145], v[200:203], v[104:107]
	v_mfma_f32_16x16x32_bf16 v[100:103], v[156:159], v[200:203], v[100:103]
	v_mfma_f32_16x16x32_bf16 v[88:91], v[142:145], v[216:219], v[88:91]
	v_mfma_f32_16x16x32_bf16 v[84:87], v[156:159], v[216:219], v[84:87]
	v_mfma_f32_16x16x32_bf16 v[72:75], v[142:145], v[224:227], v[72:75]
	v_mfma_f32_16x16x32_bf16 v[68:71], v[156:159], v[224:227], v[68:71]
	v_mfma_f32_16x16x32_bf16 v[120:123], v[152:155], v[196:199], v[120:123]
	v_mfma_f32_16x16x32_bf16 v[116:119], v[172:175], v[196:199], v[116:119]
	v_mfma_f32_16x16x32_bf16 v[104:107], v[152:155], v[212:215], v[104:107]
	v_mfma_f32_16x16x32_bf16 v[100:103], v[172:175], v[212:215], v[100:103]
	v_mfma_f32_16x16x32_bf16 v[88:91], v[152:155], v[220:223], v[88:91]
	v_mfma_f32_16x16x32_bf16 v[84:87], v[172:175], v[220:223], v[84:87]
	v_mfma_f32_16x16x32_bf16 v[72:75], v[152:155], v[228:231], v[72:75]
	v_mfma_f32_16x16x32_bf16 v[68:71], v[172:175], v[228:231], v[68:71]
	v_mfma_f32_16x16x32_bf16 v[128:131], v[176:179], v[192:195], v[128:131]
	v_mfma_f32_16x16x32_bf16 v[124:127], v[184:187], v[192:195], v[124:127]
	v_mfma_f32_16x16x32_bf16 v[112:115], v[176:179], v[200:203], v[112:115]
	v_mfma_f32_16x16x32_bf16 v[108:111], v[184:187], v[200:203], v[108:111]
	v_mfma_f32_16x16x32_bf16 v[96:99], v[176:179], v[216:219], v[96:99]
	v_mfma_f32_16x16x32_bf16 v[92:95], v[184:187], v[216:219], v[92:95]
	v_mfma_f32_16x16x32_bf16 v[80:83], v[176:179], v[224:227], v[80:83]
	v_mfma_f32_16x16x32_bf16 v[76:79], v[184:187], v[224:227], v[76:79]
	v_mfma_f32_16x16x32_bf16 v[128:131], v[180:183], v[196:199], v[128:131]
	v_mfma_f32_16x16x32_bf16 v[124:127], v[188:191], v[196:199], v[124:127]
	v_mfma_f32_16x16x32_bf16 v[112:115], v[180:183], v[212:215], v[112:115]
	v_mfma_f32_16x16x32_bf16 v[108:111], v[188:191], v[212:215], v[108:111]
	v_mfma_f32_16x16x32_bf16 v[96:99], v[180:183], v[220:223], v[96:99]
	v_mfma_f32_16x16x32_bf16 v[92:95], v[188:191], v[220:223], v[92:95]
	v_mfma_f32_16x16x32_bf16 v[80:83], v[180:183], v[228:231], v[80:83]
	v_mfma_f32_16x16x32_bf16 v[76:79], v[188:191], v[228:231], v[76:79]
	s_barrier
	s_add_i32 s40, s57, s42
	s_mov_b32 m0, s40
	ds_read_b128 v[192:195], v150 offset:49152
	ds_read_b128 v[196:199], v150 offset:50176
	ds_read_b128 v[200:203], v150 offset:51200
	ds_read_b128 v[212:215], v150 offset:52224
	ds_read_b128 v[216:219], v150 offset:53248
	ds_read_b128 v[220:223], v150 offset:54272
	ds_read_b128 v[224:227], v150 offset:55296
	ds_read_b128 v[228:231], v150 offset:56320
	global_load_lds_dwordx4 v134, s[98:99]
	s_add_i32 m0, s40, 0x2000
	s_add_u32 s36, s36, 0x80080
	s_addc_u32 s37, s37, 0
	s_add_i32 s40, s58, s42
	global_load_lds_dwordx4 v0, s[98:99]
	s_mov_b32 m0, s40
	s_nop 0
	global_load_lds_dwordx4 v134, s[36:37]
	s_add_i32 m0, s40, 0x2000
	s_nop 0
	global_load_lds_dwordx4 v0, s[36:37]
	s_mov_b32 m0, s49
	s_nop 0
	global_load_lds_dwordx4 v136, s[100:101]
	s_mov_b32 m0, s50
	s_nop 0
	global_load_lds_dwordx4 v132, s[100:101]
	s_waitcnt vmcnt(8)
	s_waitcnt lgkmcnt(0)
	s_barrier
	s_waitcnt lgkmcnt(0)
	v_mfma_f32_16x16x32_bf16 v[56:59], v[142:145], v[192:195], v[56:59]
	v_mfma_f32_16x16x32_bf16 v[52:55], v[156:159], v[192:195], v[52:55]
	v_mfma_f32_16x16x32_bf16 v[40:43], v[142:145], v[200:203], v[40:43]
	v_mfma_f32_16x16x32_bf16 v[36:39], v[156:159], v[200:203], v[36:39]
	v_mfma_f32_16x16x32_bf16 v[24:27], v[142:145], v[216:219], v[24:27]
	v_mfma_f32_16x16x32_bf16 v[20:23], v[156:159], v[216:219], v[20:23]
	v_mfma_f32_16x16x32_bf16 v[8:11], v[142:145], v[224:227], v[8:11]
	v_mfma_f32_16x16x32_bf16 v[4:7], v[156:159], v[224:227], v[4:7]
	v_mfma_f32_16x16x32_bf16 v[56:59], v[152:155], v[196:199], v[56:59]
	v_mfma_f32_16x16x32_bf16 v[52:55], v[172:175], v[196:199], v[52:55]
	v_mfma_f32_16x16x32_bf16 v[40:43], v[152:155], v[212:215], v[40:43]
	v_mfma_f32_16x16x32_bf16 v[36:39], v[172:175], v[212:215], v[36:39]
	v_mfma_f32_16x16x32_bf16 v[24:27], v[152:155], v[220:223], v[24:27]
	v_mfma_f32_16x16x32_bf16 v[20:23], v[172:175], v[220:223], v[20:23]
	v_mfma_f32_16x16x32_bf16 v[8:11], v[152:155], v[228:231], v[8:11]
	v_mfma_f32_16x16x32_bf16 v[4:7], v[172:175], v[228:231], v[4:7]
	v_mfma_f32_16x16x32_bf16 v[64:67], v[176:179], v[192:195], v[64:67]
	v_mfma_f32_16x16x32_bf16 v[60:63], v[184:187], v[192:195], v[60:63]
	v_mfma_f32_16x16x32_bf16 v[48:51], v[176:179], v[200:203], v[48:51]
	v_mfma_f32_16x16x32_bf16 v[44:47], v[184:187], v[200:203], v[44:47]
	v_mfma_f32_16x16x32_bf16 v[32:35], v[176:179], v[216:219], v[32:35]
	v_mfma_f32_16x16x32_bf16 v[28:31], v[184:187], v[216:219], v[28:31]
	v_mfma_f32_16x16x32_bf16 v[16:19], v[176:179], v[224:227], v[16:19]
	v_mfma_f32_16x16x32_bf16 v[12:15], v[184:187], v[224:227], v[12:15]
	v_mfma_f32_16x16x32_bf16 v[64:67], v[180:183], v[196:199], v[64:67]
	v_mfma_f32_16x16x32_bf16 v[60:63], v[188:191], v[196:199], v[60:63]
	v_mfma_f32_16x16x32_bf16 v[48:51], v[180:183], v[212:215], v[48:51]
	v_mfma_f32_16x16x32_bf16 v[44:47], v[188:191], v[212:215], v[44:47]
	v_mfma_f32_16x16x32_bf16 v[32:35], v[180:183], v[220:223], v[32:35]
	v_mfma_f32_16x16x32_bf16 v[28:31], v[188:191], v[220:223], v[28:31]
	v_mfma_f32_16x16x32_bf16 v[16:19], v[180:183], v[228:231], v[16:19]
	v_mfma_f32_16x16x32_bf16 v[12:15], v[188:191], v[228:231], v[12:15]
	s_barrier
	s_add_i32 s56, s56, 2
	s_add_u32 s2, s2, 0x100
	s_addc_u32 s3, s3, 0
	s_cmp_gt_u32 s56, 29
	s_cbranch_scc0 .LBB0_1051
	s_and_b64 vcc, exec, s[10:11]
	s_cbranch_vccz .LBB0_1054
	s_barrier
; __device__ __forceinline__ float ss_get(const ss_t* p) { const ss_t v = *p; return (float)(unsigned)(v >> 32) + (float)(unsigned)v * 2.3283064365386963e-10f; }
; __device__ __forceinline__ unsigned pkbf(float lo, float hi) { typedef float f2_t __attribute__((ext_vector_type(2))); typedef __bf16 b2_t __attribute__((ext_vector_type(2))); f2_t v = {lo, hi}; b2_t b = __builtin_convertvector(v, b2_t); return __builtin_bit_cast(unsigned, b); }
; __device__ __forceinline__ f32x2 swiglu_pk(f32x2 g, f32x2 u, float c1, float rs2) {
;     const f32x2 z = g * c1; f32x2 e; e.x = __builtin_amdgcn_exp2f(z.x); e.y = __builtin_amdgcn_exp2f(z.y);
;     const f32x2 d = e + 1.0f; f32x2 r; r.x = __builtin_amdgcn_rcpf(d.x); r.y = __builtin_amdgcn_rcpf(d.y);
;     return (g * u) * (r * rs2);
; }
;     __device__ __forceinline__ void operator()(const f32x4 (&acc)[2][2][4][2], const Unit& u, int wr, int wc, int fr, int fq) const {
;         int row0 = u.pm * BM + wr * 64 + fr; asm volatile("" : "+v"(row0));     const int col0 = u.pn * HALF + wc * 32 + 8 * fq;
; #pragma unroll
;         for (int ai = 0; ai < 2; ++ai)
; #pragma unroll
;             for (int m = 0; m < 4; ++m) { const int row = row0 + ai * HALF + m * 16; bf16_t* rowp = O + (size_t)row * ldc + col0;
;                 const float rs = 1.0f / sqrtf(ss_get(ssq + row) * (1.0f / 2048.f) + 1e-6f);
;                 const float c1 = -1.4426950408889634f * rs, rs2 = rs * rs;
;                 const f32x4 ga = acc[ai][0][m][0], gb = acc[ai][0][m][1], ua = acc[ai][1][m][0], ub = acc[ai][1][m][1];
;                 u32x4 w;
;                 { const f32x2 o = swiglu_pk((f32x2){ga[0], ga[1]}, (f32x2){ua[0], ua[1]}, c1, rs2); w.x = pkbf(o.x, o.y); }
;                 { const f32x2 o = swiglu_pk((f32x2){ga[2], ga[3]}, (f32x2){ua[2], ua[3]}, c1, rs2); w.y = pkbf(o.x, o.y); }
;                 { const f32x2 o = swiglu_pk((f32x2){gb[0], gb[1]}, (f32x2){ub[0], ub[1]}, c1, rs2); w.z = pkbf(o.x, o.y); }
;                 { const f32x2 o = swiglu_pk((f32x2){gb[2], gb[3]}, (f32x2){ub[2], ub[3]}, c1, rs2); w.w = pkbf(o.x, o.y); }
;                 *(u32x4*)rowp = w; }
.LBB0_1054:
	s_setprio 0
	v_mov_b32_e32 v142, v148
	v_readlane_b32 s2, v247, 4
	v_ashrrev_i32_e32 v143, 31, v142
	v_lshl_add_u64 v[146:147], v[142:143], 3, s[4:5]
	v_readlane_b32 s3, v247, 5
	v_mov_b32_e32 v157, v2
	v_pk_mul_f32 v[158:159], v[116:117], v[124:125]
	v_mov_b64_e32 v[144:145], s[2:3]
	s_flbit_i32_b32 s2, 0
	s_min_u32 s13, s2, 32
	s_sub_i32 s36, 32, s13
	v_lshl_or_b32 v154, s52, 7, v149
	v_ashrrev_i32_e32 v155, 31, v154
	s_movk_i32 s16, 0x2c00
	v_pk_mul_f32 v[130:131], v[122:123], v[130:131]
	v_pk_mul_f32 v[128:129], v[120:121], v[128:129]
	v_pk_mul_f32 v[126:127], v[118:119], v[126:127]
	v_pk_mul_f32 v[114:115], v[106:107], v[114:115]
	v_pk_mul_f32 v[112:113], v[104:105], v[112:113]
	v_pk_mul_f32 v[110:111], v[102:103], v[110:111]
	v_pk_mul_f32 v[108:109], v[100:101], v[108:109]
	v_pk_mul_f32 v[98:99], v[90:91], v[98:99]
	v_pk_mul_f32 v[96:97], v[88:89], v[96:97]
	v_pk_mul_f32 v[94:95], v[86:87], v[94:95]
	v_pk_mul_f32 v[92:93], v[84:85], v[92:93]
	v_pk_mul_f32 v[82:83], v[74:75], v[82:83]
	v_pk_mul_f32 v[80:81], v[72:73], v[80:81]
	v_pk_mul_f32 v[78:79], v[70:71], v[78:79]
	v_pk_mul_f32 v[76:77], v[68:69], v[76:77]
	v_pk_mul_f32 v[66:67], v[58:59], v[66:67]
	v_pk_mul_f32 v[64:65], v[56:57], v[64:65]
	v_pk_mul_f32 v[62:63], v[54:55], v[62:63]
	v_pk_mul_f32 v[60:61], v[52:53], v[60:61]
	v_pk_mul_f32 v[50:51], v[42:43], v[50:51]
	v_pk_mul_f32 v[48:49], v[40:41], v[48:49]
	v_pk_mul_f32 v[46:47], v[38:39], v[46:47]
	v_pk_mul_f32 v[44:45], v[36:37], v[44:45]
	v_pk_mul_f32 v[34:35], v[26:27], v[34:35]
	v_pk_mul_f32 v[32:33], v[24:25], v[32:33]
	v_pk_mul_f32 v[30:31], v[22:23], v[30:31]
	v_pk_mul_f32 v[28:29], v[20:21], v[28:29]
	v_pk_mul_f32 v[18:19], v[10:11], v[18:19]
	v_pk_mul_f32 v[16:17], v[8:9], v[16:17]
	v_pk_mul_f32 v[14:15], v[6:7], v[14:15]
	v_pk_mul_f32 v[12:13], v[4:5], v[12:13]
	v_mad_i64_i32 v[152:153], s[2:3], v142, s16, v[144:145]
	s_nop 1
	v_mov_b32_e32 v143, v240
	v_lshlrev_b64 v[124:125], 1, v[154:155]
	v_lshl_add_u64 v[152:153], v[152:153], 0, v[124:125]
	s_nop 1
	s_nop 1
	s_nop 1
	v_mul_f32_e32 v154, 0xbfb8aa3b, v143
	v_pk_mul_f32 v[120:121], v[120:121], v[154:155] op_sel_hi:[1,0]
	v_pk_mul_f32 v[122:123], v[122:123], v[154:155] op_sel_hi:[1,0]
	v_pk_mul_f32 v[116:117], v[116:117], v[154:155] op_sel_hi:[1,0]
	v_pk_mul_f32 v[118:119], v[118:119], v[154:155] op_sel_hi:[1,0]
	v_exp_f32_e32 v120, v120
	v_exp_f32_e32 v121, v121
	v_exp_f32_e32 v122, v122
	v_exp_f32_e32 v123, v123
	v_exp_f32_e32 v116, v116
	v_exp_f32_e32 v117, v117
	v_exp_f32_e32 v118, v118
	v_exp_f32_e32 v119, v119
	v_pk_add_f32 v[120:121], v[120:121], 1.0 op_sel_hi:[1,0]
	v_pk_add_f32 v[122:123], v[122:123], 1.0 op_sel_hi:[1,0]
	v_pk_add_f32 v[116:117], v[116:117], 1.0 op_sel_hi:[1,0]
	v_pk_add_f32 v[118:119], v[118:119], 1.0 op_sel_hi:[1,0]
	v_rcp_f32_e32 v120, v120
	v_rcp_f32_e32 v121, v121
	v_rcp_f32_e32 v122, v122
	v_rcp_f32_e32 v123, v123
	v_rcp_f32_e32 v116, v116
	v_rcp_f32_e32 v117, v117
	v_rcp_f32_e32 v118, v118
	v_rcp_f32_e32 v119, v119
	v_mul_f32_e32 v156, v143, v143
	v_pk_mul_f32 v[120:121], v[156:157], v[120:121] op_sel_hi:[0,1]
	v_pk_mul_f32 v[122:123], v[156:157], v[122:123] op_sel_hi:[0,1]
	v_pk_mul_f32 v[116:117], v[156:157], v[116:117] op_sel_hi:[0,1]
	v_pk_mul_f32 v[118:119], v[156:157], v[118:119] op_sel_hi:[0,1]
	v_pk_mul_f32 v[120:121], v[128:129], v[120:121]
	v_pk_mul_f32 v[122:123], v[130:131], v[122:123]
	v_pk_mul_f32 v[128:129], v[158:159], v[116:117]
	v_pk_mul_f32 v[126:127], v[126:127], v[118:119]
	v_cvt_pk_bf16_f32 v116, v120, v121
	v_cvt_pk_bf16_f32 v117, v122, v123
	v_cvt_pk_bf16_f32 v118, v128, v129
	v_cvt_pk_bf16_f32 v119, v126, v127
	global_store_dwordx4 v[152:153], v[116:119], off
	s_nop 0
	s_nop 0
	v_mov_b32_e32 v119, v2
	v_mov_b32_e32 v119, v241
	s_nop 1
	v_add_u32_e32 v116, 16, v142
	v_mad_i64_i32 v[116:117], s[2:3], v116, s16, v[144:145]
	v_lshl_add_u64 v[116:117], v[116:117], 0, v[124:125]
	s_nop 0
	s_nop 1
	s_nop 1
	v_mul_f32_e32 v118, 0xbfb8aa3b, v119
	v_pk_mul_f32 v[104:105], v[104:105], v[118:119] op_sel_hi:[1,0]
	v_pk_mul_f32 v[106:107], v[106:107], v[118:119] op_sel_hi:[1,0]
	v_pk_mul_f32 v[100:101], v[100:101], v[118:119] op_sel_hi:[1,0]
	v_pk_mul_f32 v[102:103], v[102:103], v[118:119] op_sel_hi:[1,0]
	v_exp_f32_e32 v104, v104
	v_exp_f32_e32 v105, v105
	v_exp_f32_e32 v106, v106
	v_exp_f32_e32 v107, v107
	v_exp_f32_e32 v100, v100
	v_exp_f32_e32 v101, v101
	v_exp_f32_e32 v102, v102
	v_exp_f32_e32 v103, v103
	v_pk_add_f32 v[104:105], v[104:105], 1.0 op_sel_hi:[1,0]
	v_pk_add_f32 v[106:107], v[106:107], 1.0 op_sel_hi:[1,0]
	v_pk_add_f32 v[100:101], v[100:101], 1.0 op_sel_hi:[1,0]
	v_pk_add_f32 v[102:103], v[102:103], 1.0 op_sel_hi:[1,0]
	v_rcp_f32_e32 v104, v104
	v_rcp_f32_e32 v105, v105
	v_rcp_f32_e32 v106, v106
	v_rcp_f32_e32 v107, v107
	v_rcp_f32_e32 v100, v100
	v_rcp_f32_e32 v101, v101
	v_rcp_f32_e32 v102, v102
	v_rcp_f32_e32 v103, v103
	v_mul_f32_e32 v120, v119, v119
	v_pk_mul_f32 v[104:105], v[120:121], v[104:105] op_sel_hi:[0,1]
	v_pk_mul_f32 v[106:107], v[120:121], v[106:107] op_sel_hi:[0,1]
	v_pk_mul_f32 v[100:101], v[120:121], v[100:101] op_sel_hi:[0,1]
	v_pk_mul_f32 v[102:103], v[120:121], v[102:103] op_sel_hi:[0,1]
	v_pk_mul_f32 v[104:105], v[112:113], v[104:105]
	v_pk_mul_f32 v[106:107], v[114:115], v[106:107]
	v_pk_mul_f32 v[108:109], v[108:109], v[100:101]
	v_pk_mul_f32 v[110:111], v[110:111], v[102:103]
	v_cvt_pk_bf16_f32 v100, v104, v105
	v_cvt_pk_bf16_f32 v101, v106, v107
	v_cvt_pk_bf16_f32 v102, v108, v109
	v_cvt_pk_bf16_f32 v103, v110, v111
	global_store_dwordx4 v[116:117], v[100:103], off
	s_nop 0
	s_nop 0
	v_mov_b32_e32 v103, v2
	v_mov_b32_e32 v103, v242
	s_nop 1
	v_add_u32_e32 v100, 32, v142
; __device__ __forceinline__ float ss_get(const ss_t* p) { const ss_t v = *p; return (float)(unsigned)(v >> 32) + (float)(unsigned)v * 2.3283064365386963e-10f; }
; __device__ __forceinline__ unsigned pkbf(float lo, float hi) { typedef float f2_t __attribute__((ext_vector_type(2))); typedef __bf16 b2_t __attribute__((ext_vector_type(2))); f2_t v = {lo, hi}; b2_t b = __builtin_convertvector(v, b2_t); return __builtin_bit_cast(unsigned, b); }
; __device__ __forceinline__ f32x2 swiglu_pk(f32x2 g, f32x2 u, float c1, float rs2) {
;     const f32x2 z = g * c1; f32x2 e; e.x = __builtin_amdgcn_exp2f(z.x); e.y = __builtin_amdgcn_exp2f(z.y);
;     const f32x2 d = e + 1.0f; f32x2 r; r.x = __builtin_amdgcn_rcpf(d.x); r.y = __builtin_amdgcn_rcpf(d.y);
;     return (g * u) * (r * rs2);
; }
;     __device__ __forceinline__ void operator()(const f32x4 (&acc)[2][2][4][2], const Unit& u, int wr, int wc, int fr, int fq) const {
;     ...
;             for (int m = 0; m < 4; ++m) { const int row = row0 + ai * HALF + m * 16; bf16_t* rowp = O + (size_t)row * ldc + col0;
;                 const float rs = 1.0f / sqrtf(ss_get(ssq + row) * (1.0f / 2048.f) + 1e-6f);
;                 const float c1 = -1.4426950408889634f * rs, rs2 = rs * rs;
;                 const f32x4 ga = acc[ai][0][m][0], gb = acc[ai][0][m][1], ua = acc[ai][1][m][0], ub = acc[ai][1][m][1];
;                 u32x4 w;
;                 { const f32x2 o = swiglu_pk((f32x2){ga[0], ga[1]}, (f32x2){ua[0], ua[1]}, c1, rs2); w.x = pkbf(o.x, o.y); }
;                 { const f32x2 o = swiglu_pk((f32x2){ga[2], ga[3]}, (f32x2){ua[2], ua[3]}, c1, rs2); w.y = pkbf(o.x, o.y); }
;                 { const f32x2 o = swiglu_pk((f32x2){gb[0], gb[1]}, (f32x2){ub[0], ub[1]}, c1, rs2); w.z = pkbf(o.x, o.y); }
;                 { const f32x2 o = swiglu_pk((f32x2){gb[2], gb[3]}, (f32x2){ub[2], ub[3]}, c1, rs2); w.w = pkbf(o.x, o.y); }
;                 *(u32x4*)rowp = w; }
	v_mad_i64_i32 v[100:101], s[2:3], v100, s16, v[144:145]
	v_lshl_add_u64 v[100:101], v[100:101], 0, v[124:125]
	s_nop 0
	s_nop 1
	s_nop 1
	v_mul_f32_e32 v102, 0xbfb8aa3b, v103
	v_pk_mul_f32 v[88:89], v[88:89], v[102:103] op_sel_hi:[1,0]
	v_pk_mul_f32 v[90:91], v[90:91], v[102:103] op_sel_hi:[1,0]
	v_pk_mul_f32 v[84:85], v[84:85], v[102:103] op_sel_hi:[1,0]
	v_pk_mul_f32 v[86:87], v[86:87], v[102:103] op_sel_hi:[1,0]
	v_exp_f32_e32 v88, v88
	v_exp_f32_e32 v89, v89
	v_exp_f32_e32 v90, v90
	v_exp_f32_e32 v91, v91
	v_exp_f32_e32 v84, v84
	v_exp_f32_e32 v85, v85
	v_exp_f32_e32 v86, v86
	v_exp_f32_e32 v87, v87
	v_pk_add_f32 v[88:89], v[88:89], 1.0 op_sel_hi:[1,0]
	v_pk_add_f32 v[90:91], v[90:91], 1.0 op_sel_hi:[1,0]
	v_pk_add_f32 v[84:85], v[84:85], 1.0 op_sel_hi:[1,0]
	v_pk_add_f32 v[86:87], v[86:87], 1.0 op_sel_hi:[1,0]
	v_rcp_f32_e32 v88, v88
	v_rcp_f32_e32 v89, v89
	v_rcp_f32_e32 v90, v90
	v_rcp_f32_e32 v91, v91
	v_rcp_f32_e32 v84, v84
	v_rcp_f32_e32 v85, v85
	v_rcp_f32_e32 v86, v86
	v_rcp_f32_e32 v87, v87
	v_mul_f32_e32 v104, v103, v103
	v_pk_mul_f32 v[88:89], v[104:105], v[88:89] op_sel_hi:[0,1]
	v_pk_mul_f32 v[90:91], v[104:105], v[90:91] op_sel_hi:[0,1]
	v_pk_mul_f32 v[84:85], v[104:105], v[84:85] op_sel_hi:[0,1]
	v_pk_mul_f32 v[86:87], v[104:105], v[86:87] op_sel_hi:[0,1]
	v_pk_mul_f32 v[88:89], v[96:97], v[88:89]
	v_pk_mul_f32 v[90:91], v[98:99], v[90:91]
	v_pk_mul_f32 v[92:93], v[92:93], v[84:85]
	v_pk_mul_f32 v[94:95], v[94:95], v[86:87]
	v_cvt_pk_bf16_f32 v84, v88, v89
	v_cvt_pk_bf16_f32 v85, v90, v91
	v_cvt_pk_bf16_f32 v86, v92, v93
	v_cvt_pk_bf16_f32 v87, v94, v95
	global_store_dwordx4 v[100:101], v[84:87], off
	s_nop 0
	s_nop 0
	v_mov_b32_e32 v87, v2
	v_mov_b32_e32 v87, v243
	s_nop 1
	v_add_u32_e32 v84, 48, v142
	v_mad_i64_i32 v[84:85], s[2:3], v84, s16, v[144:145]
	v_lshl_add_u64 v[84:85], v[84:85], 0, v[124:125]
	s_nop 0
	s_nop 1
	s_nop 1
	v_mul_f32_e32 v86, 0xbfb8aa3b, v87
	v_pk_mul_f32 v[72:73], v[72:73], v[86:87] op_sel_hi:[1,0]
	v_pk_mul_f32 v[74:75], v[74:75], v[86:87] op_sel_hi:[1,0]
	v_pk_mul_f32 v[68:69], v[68:69], v[86:87] op_sel_hi:[1,0]
	v_pk_mul_f32 v[70:71], v[70:71], v[86:87] op_sel_hi:[1,0]
	v_exp_f32_e32 v72, v72
	v_exp_f32_e32 v73, v73
	v_exp_f32_e32 v74, v74
	v_exp_f32_e32 v75, v75
	v_exp_f32_e32 v68, v68
	v_exp_f32_e32 v69, v69
	v_exp_f32_e32 v70, v70
	v_exp_f32_e32 v71, v71
	v_pk_add_f32 v[72:73], v[72:73], 1.0 op_sel_hi:[1,0]
	v_pk_add_f32 v[74:75], v[74:75], 1.0 op_sel_hi:[1,0]
	v_pk_add_f32 v[68:69], v[68:69], 1.0 op_sel_hi:[1,0]
	v_pk_add_f32 v[70:71], v[70:71], 1.0 op_sel_hi:[1,0]
	v_rcp_f32_e32 v72, v72
	v_rcp_f32_e32 v73, v73
	v_rcp_f32_e32 v74, v74
	v_rcp_f32_e32 v75, v75
	v_rcp_f32_e32 v68, v68
	v_rcp_f32_e32 v69, v69
	v_rcp_f32_e32 v70, v70
	v_rcp_f32_e32 v71, v71
	v_mul_f32_e32 v88, v87, v87
	v_pk_mul_f32 v[72:73], v[88:89], v[72:73] op_sel_hi:[0,1]
	v_pk_mul_f32 v[74:75], v[88:89], v[74:75] op_sel_hi:[0,1]
	v_pk_mul_f32 v[68:69], v[88:89], v[68:69] op_sel_hi:[0,1]
	v_pk_mul_f32 v[70:71], v[88:89], v[70:71] op_sel_hi:[0,1]
	v_pk_mul_f32 v[72:73], v[80:81], v[72:73]
	v_pk_mul_f32 v[74:75], v[82:83], v[74:75]
	v_pk_mul_f32 v[76:77], v[76:77], v[68:69]
	v_pk_mul_f32 v[78:79], v[78:79], v[70:71]
	v_cvt_pk_bf16_f32 v68, v72, v73
	v_cvt_pk_bf16_f32 v69, v74, v75
	v_cvt_pk_bf16_f32 v70, v76, v77
	v_cvt_pk_bf16_f32 v71, v78, v79
	global_store_dwordx4 v[84:85], v[68:71], off
	s_nop 0
	s_nop 0
	v_mov_b32_e32 v71, v2
	v_mov_b32_e32 v71, v244
	s_nop 1
	v_add_u32_e32 v68, 0x80, v142
	v_mad_i64_i32 v[68:69], s[2:3], v68, s16, v[144:145]
	v_lshl_add_u64 v[68:69], v[68:69], 0, v[124:125]
	s_nop 0
	s_nop 1
	s_nop 1
	v_mul_f32_e32 v70, 0xbfb8aa3b, v71
	v_pk_mul_f32 v[56:57], v[56:57], v[70:71] op_sel_hi:[1,0]
	v_pk_mul_f32 v[58:59], v[58:59], v[70:71] op_sel_hi:[1,0]
	v_pk_mul_f32 v[52:53], v[52:53], v[70:71] op_sel_hi:[1,0]
	v_pk_mul_f32 v[54:55], v[54:55], v[70:71] op_sel_hi:[1,0]
	v_exp_f32_e32 v56, v56
	v_exp_f32_e32 v57, v57
	v_exp_f32_e32 v58, v58
	v_exp_f32_e32 v59, v59
	v_exp_f32_e32 v52, v52
	v_exp_f32_e32 v53, v53
	v_exp_f32_e32 v54, v54
	v_exp_f32_e32 v55, v55
	v_pk_add_f32 v[56:57], v[56:57], 1.0 op_sel_hi:[1,0]
	v_pk_add_f32 v[58:59], v[58:59], 1.0 op_sel_hi:[1,0]
	v_pk_add_f32 v[52:53], v[52:53], 1.0 op_sel_hi:[1,0]
	v_pk_add_f32 v[54:55], v[54:55], 1.0 op_sel_hi:[1,0]
	v_rcp_f32_e32 v56, v56
	v_rcp_f32_e32 v57, v57
	v_rcp_f32_e32 v58, v58
	v_rcp_f32_e32 v59, v59
	v_rcp_f32_e32 v52, v52
	v_rcp_f32_e32 v53, v53
	v_rcp_f32_e32 v54, v54
	v_rcp_f32_e32 v55, v55
	v_mul_f32_e32 v72, v71, v71
	v_pk_mul_f32 v[56:57], v[72:73], v[56:57] op_sel_hi:[0,1]
	v_pk_mul_f32 v[58:59], v[72:73], v[58:59] op_sel_hi:[0,1]
	v_pk_mul_f32 v[52:53], v[72:73], v[52:53] op_sel_hi:[0,1]
	v_pk_mul_f32 v[54:55], v[72:73], v[54:55] op_sel_hi:[0,1]
	v_pk_mul_f32 v[56:57], v[64:65], v[56:57]
	v_pk_mul_f32 v[58:59], v[66:67], v[58:59]
	v_pk_mul_f32 v[60:61], v[60:61], v[52:53]
	v_pk_mul_f32 v[62:63], v[62:63], v[54:55]
	v_cvt_pk_bf16_f32 v52, v56, v57
	v_cvt_pk_bf16_f32 v53, v58, v59
	v_cvt_pk_bf16_f32 v54, v60, v61
	v_cvt_pk_bf16_f32 v55, v62, v63
	global_store_dwordx4 v[68:69], v[52:55], off
	s_nop 0
	s_nop 0
	v_mov_b32_e32 v55, v2
	v_mov_b32_e32 v55, v245
	s_nop 1
; __device__ __forceinline__ float ss_get(const ss_t* p) { const ss_t v = *p; return (float)(unsigned)(v >> 32) + (float)(unsigned)v * 2.3283064365386963e-10f; }
; __device__ __forceinline__ unsigned pkbf(float lo, float hi) { typedef float f2_t __attribute__((ext_vector_type(2))); typedef __bf16 b2_t __attribute__((ext_vector_type(2))); f2_t v = {lo, hi}; b2_t b = __builtin_convertvector(v, b2_t); return __builtin_bit_cast(unsigned, b); }
;     __device__ __forceinline__ void operator()(const f32x4 (&acc)[2][2][4][2], const Unit& u, int wr, int wc, int fr, int fq) const {
;     ...
;             for (int m = 0; m < 4; ++m) { const int row = row0 + ai * HALF + m * 16; bf16_t* rowp = O + (size_t)row * ldc + col0;
;                 const float rs = 1.0f / sqrtf(ss_get(ssq + row) * (1.0f / 2048.f) + 1e-6f);
;                 const float c1 = -1.4426950408889634f * rs, rs2 = rs * rs;
;                 const f32x4 ga = acc[ai][0][m][0], gb = acc[ai][0][m][1], ua = acc[ai][1][m][0], ub = acc[ai][1][m][1];
;                 u32x4 w;
;                 { const f32x2 o = swiglu_pk((f32x2){ga[0], ga[1]}, (f32x2){ua[0], ua[1]}, c1, rs2); w.x = pkbf(o.x, o.y); }
;                 { const f32x2 o = swiglu_pk((f32x2){ga[2], ga[3]}, (f32x2){ua[2], ua[3]}, c1, rs2); w.y = pkbf(o.x, o.y); }
;                 { const f32x2 o = swiglu_pk((f32x2){gb[0], gb[1]}, (f32x2){ub[0], ub[1]}, c1, rs2); w.z = pkbf(o.x, o.y); }
;                 { const f32x2 o = swiglu_pk((f32x2){gb[2], gb[3]}, (f32x2){ub[2], ub[3]}, c1, rs2); w.w = pkbf(o.x, o.y); }
;                 *(u32x4*)rowp = w; }
; template <class Epi, class Sched, bool ALIGN_EPI = false, bool SP2 = false>
; __device__ __forceinline__ void gemm_phase(PG8_LAS unsigned char* lds, const Gemm g, const Sched& S, const Epi& E) {
;     ...
;         if (!has_next) break;
	v_add_u32_e32 v52, 0x90, v142
	v_mad_i64_i32 v[52:53], s[2:3], v52, s16, v[144:145]
	v_lshl_add_u64 v[52:53], v[52:53], 0, v[124:125]
	s_nop 0
	s_nop 1
	s_nop 1
	v_mul_f32_e32 v54, 0xbfb8aa3b, v55
	v_pk_mul_f32 v[40:41], v[40:41], v[54:55] op_sel_hi:[1,0]
	v_pk_mul_f32 v[42:43], v[42:43], v[54:55] op_sel_hi:[1,0]
	v_pk_mul_f32 v[36:37], v[36:37], v[54:55] op_sel_hi:[1,0]
	v_pk_mul_f32 v[38:39], v[38:39], v[54:55] op_sel_hi:[1,0]
	v_exp_f32_e32 v40, v40
	v_exp_f32_e32 v41, v41
	v_exp_f32_e32 v42, v42
	v_exp_f32_e32 v43, v43
	v_exp_f32_e32 v36, v36
	v_exp_f32_e32 v37, v37
	v_exp_f32_e32 v38, v38
	v_exp_f32_e32 v39, v39
	v_pk_add_f32 v[40:41], v[40:41], 1.0 op_sel_hi:[1,0]
	v_pk_add_f32 v[42:43], v[42:43], 1.0 op_sel_hi:[1,0]
	v_pk_add_f32 v[36:37], v[36:37], 1.0 op_sel_hi:[1,0]
	v_pk_add_f32 v[38:39], v[38:39], 1.0 op_sel_hi:[1,0]
	v_rcp_f32_e32 v40, v40
	v_rcp_f32_e32 v41, v41
	v_rcp_f32_e32 v42, v42
	v_rcp_f32_e32 v43, v43
	v_rcp_f32_e32 v36, v36
	v_rcp_f32_e32 v37, v37
	v_rcp_f32_e32 v38, v38
	v_rcp_f32_e32 v39, v39
	v_mul_f32_e32 v56, v55, v55
	v_pk_mul_f32 v[40:41], v[56:57], v[40:41] op_sel_hi:[0,1]
	v_pk_mul_f32 v[42:43], v[56:57], v[42:43] op_sel_hi:[0,1]
	v_pk_mul_f32 v[36:37], v[56:57], v[36:37] op_sel_hi:[0,1]
	v_pk_mul_f32 v[38:39], v[56:57], v[38:39] op_sel_hi:[0,1]
	v_pk_mul_f32 v[40:41], v[48:49], v[40:41]
	v_pk_mul_f32 v[42:43], v[50:51], v[42:43]
	v_pk_mul_f32 v[44:45], v[44:45], v[36:37]
	v_pk_mul_f32 v[46:47], v[46:47], v[38:39]
	v_cvt_pk_bf16_f32 v36, v40, v41
	v_cvt_pk_bf16_f32 v37, v42, v43
	v_cvt_pk_bf16_f32 v38, v44, v45
	v_cvt_pk_bf16_f32 v39, v46, v47
	global_store_dwordx4 v[52:53], v[36:39], off
	s_nop 0
	s_nop 0
	v_mov_b32_e32 v39, v2
	v_mov_b32_e32 v39, v246
	s_nop 1
	v_add_u32_e32 v36, 0xa0, v142
	v_mad_i64_i32 v[36:37], s[2:3], v36, s16, v[144:145]
	v_lshl_add_u64 v[36:37], v[36:37], 0, v[124:125]
	s_nop 0
	s_nop 1
	s_nop 1
	v_mul_f32_e32 v38, 0xbfb8aa3b, v39
	v_pk_mul_f32 v[24:25], v[24:25], v[38:39] op_sel_hi:[1,0]
	v_pk_mul_f32 v[26:27], v[26:27], v[38:39] op_sel_hi:[1,0]
	v_pk_mul_f32 v[20:21], v[20:21], v[38:39] op_sel_hi:[1,0]
	v_pk_mul_f32 v[22:23], v[22:23], v[38:39] op_sel_hi:[1,0]
	v_exp_f32_e32 v24, v24
	v_exp_f32_e32 v25, v25
	v_exp_f32_e32 v26, v26
	v_exp_f32_e32 v27, v27
	v_exp_f32_e32 v20, v20
	v_exp_f32_e32 v21, v21
	v_exp_f32_e32 v22, v22
	v_exp_f32_e32 v23, v23
	v_pk_add_f32 v[24:25], v[24:25], 1.0 op_sel_hi:[1,0]
	v_pk_add_f32 v[26:27], v[26:27], 1.0 op_sel_hi:[1,0]
	v_pk_add_f32 v[20:21], v[20:21], 1.0 op_sel_hi:[1,0]
	v_pk_add_f32 v[22:23], v[22:23], 1.0 op_sel_hi:[1,0]
	v_rcp_f32_e32 v24, v24
	v_rcp_f32_e32 v25, v25
	v_rcp_f32_e32 v26, v26
	v_rcp_f32_e32 v27, v27
	v_rcp_f32_e32 v20, v20
	v_rcp_f32_e32 v21, v21
	v_rcp_f32_e32 v22, v22
	v_rcp_f32_e32 v23, v23
	v_mul_f32_e32 v40, v39, v39
	v_pk_mul_f32 v[24:25], v[40:41], v[24:25] op_sel_hi:[0,1]
	v_pk_mul_f32 v[26:27], v[40:41], v[26:27] op_sel_hi:[0,1]
	v_pk_mul_f32 v[20:21], v[40:41], v[20:21] op_sel_hi:[0,1]
	v_pk_mul_f32 v[22:23], v[40:41], v[22:23] op_sel_hi:[0,1]
	v_pk_mul_f32 v[24:25], v[32:33], v[24:25]
	v_pk_mul_f32 v[26:27], v[34:35], v[26:27]
	v_pk_mul_f32 v[28:29], v[28:29], v[20:21]
	v_pk_mul_f32 v[30:31], v[30:31], v[22:23]
	v_cvt_pk_bf16_f32 v20, v24, v25
	v_cvt_pk_bf16_f32 v21, v26, v27
	v_cvt_pk_bf16_f32 v22, v28, v29
	v_cvt_pk_bf16_f32 v23, v30, v31
	global_store_dwordx4 v[36:37], v[20:23], off
	s_nop 0
	s_nop 0
	v_mov_b32_e32 v23, v2
	v_mov_b32_e32 v23, v252
	s_nop 1
	v_add_u32_e32 v20, 0xb0, v142
	v_mad_i64_i32 v[20:21], s[2:3], v20, s16, v[144:145]
	v_lshl_add_u64 v[20:21], v[20:21], 0, v[124:125]
	s_nop 0
	s_nop 1
	s_nop 1
	s_mov_b64 s[2:3], -1
	v_mul_f32_e32 v22, 0xbfb8aa3b, v23
	v_pk_mul_f32 v[8:9], v[8:9], v[22:23] op_sel_hi:[1,0]
	v_pk_mul_f32 v[10:11], v[10:11], v[22:23] op_sel_hi:[1,0]
	v_pk_mul_f32 v[4:5], v[4:5], v[22:23] op_sel_hi:[1,0]
	v_pk_mul_f32 v[6:7], v[6:7], v[22:23] op_sel_hi:[1,0]
	v_exp_f32_e32 v8, v8
	v_exp_f32_e32 v9, v9
	v_exp_f32_e32 v10, v10
	v_exp_f32_e32 v11, v11
	v_exp_f32_e32 v4, v4
	v_exp_f32_e32 v5, v5
	v_exp_f32_e32 v6, v6
	v_exp_f32_e32 v7, v7
	v_pk_add_f32 v[8:9], v[8:9], 1.0 op_sel_hi:[1,0]
	v_pk_add_f32 v[10:11], v[10:11], 1.0 op_sel_hi:[1,0]
	v_pk_add_f32 v[4:5], v[4:5], 1.0 op_sel_hi:[1,0]
	v_pk_add_f32 v[6:7], v[6:7], 1.0 op_sel_hi:[1,0]
	v_rcp_f32_e32 v8, v8
	v_rcp_f32_e32 v9, v9
	v_rcp_f32_e32 v10, v10
	v_rcp_f32_e32 v11, v11
	v_rcp_f32_e32 v4, v4
	v_rcp_f32_e32 v5, v5
	v_rcp_f32_e32 v6, v6
	v_rcp_f32_e32 v7, v7
	v_mul_f32_e32 v24, v23, v23
	v_pk_mul_f32 v[8:9], v[24:25], v[8:9] op_sel_hi:[0,1]
	v_pk_mul_f32 v[10:11], v[24:25], v[10:11] op_sel_hi:[0,1]
	v_pk_mul_f32 v[4:5], v[24:25], v[4:5] op_sel_hi:[0,1]
	v_pk_mul_f32 v[6:7], v[24:25], v[6:7] op_sel_hi:[0,1]
	v_pk_mul_f32 v[8:9], v[16:17], v[8:9]
	v_pk_mul_f32 v[10:11], v[18:19], v[10:11]
	v_pk_mul_f32 v[12:13], v[12:13], v[4:5]
	v_pk_mul_f32 v[14:15], v[14:15], v[6:7]
	s_andn2_b64 vcc, exec, s[14:15]
	v_cvt_pk_bf16_f32 v4, v8, v9
	v_cvt_pk_bf16_f32 v5, v10, v11
	v_cvt_pk_bf16_f32 v6, v12, v13
	v_cvt_pk_bf16_f32 v7, v14, v15
	global_store_dwordx4 v[20:21], v[4:7], off
	s_cbranch_vccnz .LBB0_1049
	s_andn2_b64 vcc, exec, s[8:9]
	s_cbranch_vccnz .LBB0_1048
	s_barrier
	s_branch .LBB0_1048

; #define PG8_STAGE(bufoff, gbase, voff) do { _Pragma("unroll") for (int _i = 0; _i < 2; ++_i) \
;         __builtin_amdgcn_global_load_lds((const unsigned*)((const char*)(gbase) + (voff)[_i]), (PG8_LAS unsigned*)(lds + (bufoff) + ldsw + _i * 8192), 16, 0, 0); } while (0)
; #define PG8_LDA(dst, b, h) do { _Pragma("unroll") for (int m = 0; m < 4; ++m) _Pragma("unroll") for (int k = 0; k < 2; ++k) dst[m][k] = *(const PG8_LAS bf16x8*)(lds + PG8_SA(b, h) + aoff + m * 2048 + k * 1024); } while (0)
; #define PG8_LDB(dst, b, h) do { _Pragma("unroll") for (int n = 0; n < 2; ++n) _Pragma("unroll") for (int k = 0; k < 2; ++k) dst[n][k] = *(const PG8_LAS bf16x8*)(lds + PG8_SB(b, h) + boff + n * 2048 + k * 1024); } while (0)
; #define PG8_SCHED __builtin_amdgcn_sched_barrier(0)
; template <class Epi, class Sched, bool ALIGN_EPI = false, bool SP2 = false>
; __device__ __forceinline__ void gemm_phase(PG8_LAS unsigned char* lds, const Gemm g, const Sched& S, const Epi& E) {
;     ...
;     for (;;) {
;         const bool has_next = S.next(ui + 1, nxt);
;         const char* nA = has_next ? (const char*)g.A + (size_t)nxt.pm * tstep : cA; const char* nB = has_next ? (const char*)g.Bt + (size_t)nxt.pn * tstep : cB;
;         for (int t = 0; t < nt; t += 2) {
;             const bool last = (t == nt - 2);
;             const char* a1 = cA + (size_t)(t + 1) * kstep;
;             const char* a2 = last ? nA : cA + (size_t)(t + 2) * kstep; const char* b2 = last ? nB : cB + (size_t)(t + 2) * kstep;
;             const char* a3 = a2 + kstep; const char* b3 = b2 + kstep;
;             if (last && has_next) S.a_ready(nxt);
;             if constexpr (Epi::KSPLIT) { if (t == (nt >> 1)) E.mid(acc, cur, wr, wc, fr, fq); }
;             if constexpr (SP2) {
;             PG8_LDB(B0, 0, 0); PG8_LDB(B1, 0, 1); PG8_SCHED; PG8_LDA(At, 0, 0); PG8_STAGE(PG8_SA(1, 1), a1 + hstep, voffA);
;     ...
;         for (int a = 0; a < 2; ++a)
; #pragma unroll
;             for (int b = 0; b < 2; ++b)
; #pragma unroll
;                 for (int m = 0; m < 4; ++m)
; #pragma unroll
;                     for (int n = 0; n < 2; ++n) acc[a][b][m][n] = (f32x4){0.f, 0.f, 0.f, 0.f};
.LBB0_1277:
	s_add_u32 s61, s2, 0x100
	v_mov_b32_e32 v4, 0
	s_addc_u32 s66, s3, 0
	s_mov_b32 s67, -2
	s_mov_b64 s[2:3], 0
	s_waitcnt lgkmcnt(0)
	v_mov_b32_e32 v5, v4
	v_mov_b32_e32 v6, v4
	v_mov_b32_e32 v7, v4
	v_mov_b32_e32 v8, v4
	v_mov_b32_e32 v9, v4
	v_mov_b32_e32 v10, v4
	v_mov_b32_e32 v11, v4
	v_mov_b32_e32 v20, v4
	v_mov_b32_e32 v21, v4
	v_mov_b32_e32 v22, v4
	v_mov_b32_e32 v23, v4
	v_mov_b32_e32 v24, v4
	v_mov_b32_e32 v25, v4
	v_mov_b32_e32 v26, v4
	v_mov_b32_e32 v27, v4
	v_mov_b32_e32 v36, v4
	v_mov_b32_e32 v37, v4
	v_mov_b32_e32 v38, v4
	v_mov_b32_e32 v39, v4
	v_mov_b32_e32 v40, v4
	v_mov_b32_e32 v41, v4
	v_mov_b32_e32 v42, v4
	v_mov_b32_e32 v43, v4
	v_mov_b32_e32 v52, v4
	v_mov_b32_e32 v53, v4
	v_mov_b32_e32 v54, v4
	v_mov_b32_e32 v55, v4
	v_mov_b32_e32 v56, v4
	v_mov_b32_e32 v57, v4
	v_mov_b32_e32 v58, v4
	v_mov_b32_e32 v59, v4
	v_mov_b32_e32 v12, v4
	v_mov_b32_e32 v13, v4
	v_mov_b32_e32 v14, v4
	v_mov_b32_e32 v15, v4
	v_mov_b32_e32 v16, v4
	v_mov_b32_e32 v17, v4
	v_mov_b32_e32 v18, v4
	v_mov_b32_e32 v19, v4
	v_mov_b32_e32 v28, v4
	v_mov_b32_e32 v29, v4
	v_mov_b32_e32 v30, v4
	v_mov_b32_e32 v31, v4
	v_mov_b32_e32 v32, v4
	v_mov_b32_e32 v33, v4
	v_mov_b32_e32 v34, v4
	v_mov_b32_e32 v35, v4
	v_mov_b32_e32 v44, v4
	v_mov_b32_e32 v45, v4
	v_mov_b32_e32 v46, v4
	v_mov_b32_e32 v47, v4
	v_mov_b32_e32 v48, v4
	v_mov_b32_e32 v49, v4
	v_mov_b32_e32 v50, v4
	v_mov_b32_e32 v51, v4
	v_mov_b32_e32 v60, v4
	v_mov_b32_e32 v61, v4
	v_mov_b32_e32 v62, v4
	v_mov_b32_e32 v63, v4
	v_mov_b32_e32 v64, v4
	v_mov_b32_e32 v65, v4
	v_mov_b32_e32 v66, v4
	v_mov_b32_e32 v67, v4
	v_mov_b32_e32 v68, v4
	v_mov_b32_e32 v69, v4
	v_mov_b32_e32 v70, v4
	v_mov_b32_e32 v71, v4
	v_mov_b32_e32 v72, v4
	v_mov_b32_e32 v73, v4
	v_mov_b32_e32 v74, v4
	v_mov_b32_e32 v75, v4
	v_mov_b32_e32 v84, v4
	v_mov_b32_e32 v85, v4
	v_mov_b32_e32 v86, v4
	v_mov_b32_e32 v87, v4
	v_mov_b32_e32 v88, v4
	v_mov_b32_e32 v89, v4
	v_mov_b32_e32 v90, v4
	v_mov_b32_e32 v91, v4
	v_mov_b32_e32 v100, v4
	v_mov_b32_e32 v101, v4
	v_mov_b32_e32 v102, v4
	v_mov_b32_e32 v103, v4
	v_mov_b32_e32 v104, v4
	v_mov_b32_e32 v105, v4
	v_mov_b32_e32 v106, v4
	v_mov_b32_e32 v107, v4
	v_mov_b32_e32 v116, v4
	v_mov_b32_e32 v117, v4
	v_mov_b32_e32 v118, v4
	v_mov_b32_e32 v119, v4
	v_mov_b32_e32 v120, v4
	v_mov_b32_e32 v121, v4
	v_mov_b32_e32 v122, v4
	v_mov_b32_e32 v123, v4
	v_mov_b32_e32 v76, v4
	v_mov_b32_e32 v77, v4
	v_mov_b32_e32 v78, v4
	v_mov_b32_e32 v79, v4
	v_mov_b32_e32 v80, v4
	v_mov_b32_e32 v81, v4
	v_mov_b32_e32 v82, v4
	v_mov_b32_e32 v83, v4
	v_mov_b32_e32 v92, v4
	v_mov_b32_e32 v93, v4
	v_mov_b32_e32 v94, v4
	v_mov_b32_e32 v95, v4
	v_mov_b32_e32 v96, v4
	v_mov_b32_e32 v97, v4
	v_mov_b32_e32 v98, v4
	v_mov_b32_e32 v99, v4
	v_mov_b32_e32 v108, v4
	v_mov_b32_e32 v109, v4
	v_mov_b32_e32 v110, v4
	v_mov_b32_e32 v111, v4
	v_mov_b32_e32 v112, v4
	v_mov_b32_e32 v113, v4
	v_mov_b32_e32 v114, v4
	v_mov_b32_e32 v115, v4
	v_mov_b32_e32 v128, v4
	v_mov_b32_e32 v129, v4
	v_mov_b32_e32 v130, v4
	v_mov_b32_e32 v131, v4
	v_mov_b32_e32 v132, v4
	v_mov_b32_e32 v133, v4
	v_mov_b32_e32 v134, v4
	v_mov_b32_e32 v135, v4
	v_add_u32_e32 v168, 0x10000, v3
	v_add_u32_e32 v169, 0x14000, v3
	v_add_u32_e32 v170, 0x18000, v3
	v_add_u32_e32 v171, 0x1c000, v3
	s_cmp_lg_u64 s[12:13], 0
	s_cbranch_scc1 .Lprio_P5
	s_setprio 1
.Lprio_P5:
.LBB0_1278:
	s_add_u32 s38, s93, s2
	s_addc_u32 s39, s95, s3
	s_add_u32 s38, s38, 0x1da00100
	s_addc_u32 s39, s39, 0
	s_add_u32 s68, s61, s2
	s_addc_u32 s69, s66, s3
	s_add_i32 s70, 0, 0x10000
	s_cmpk_eq_i32 s2, 0x2b00
	s_cselect_b32 s47, s35, s39
	s_cselect_b32 s46, s34, s38
	s_cselect_b32 s39, s43, s69
	s_cselect_b32 s38, s42, s68
	s_add_i32 s71, 0, 0x14000
	ds_read_b128 v[124:127], v168
	ds_read_b128 v[136:139], v168 offset:1024
	ds_read_b128 v[140:143], v168 offset:2048
	ds_read_b128 v[144:147], v168 offset:3072
	ds_read_b128 v[148:151], v169
	ds_read_b128 v[152:155], v169 offset:1024
	ds_read_b128 v[156:159], v169 offset:2048
	ds_read_b128 v[182:185], v169 offset:3072
	v_lshl_add_u64 v[202:203], v[178:179], 0, s[2:3]
	s_add_i32 m0, s49, 0xc000
	ds_read_b128 v[186:189], v214
	ds_read_b128 v[190:193], v214 offset:1024
	ds_read_b128 v[194:197], v214 offset:2048
	ds_read_b128 v[198:201], v214 offset:3072
	ds_read_b128 v[216:219], v214 offset:4096
	ds_read_b128 v[220:223], v214 offset:5120
	ds_read_b128 v[224:227], v214 offset:6144
	ds_read_b128 v[228:231], v214 offset:7168
	global_load_lds_dwordx4 v[202:203], off
	v_lshl_add_u64 v[202:203], v[180:181], 0, s[2:3]
	s_add_i32 m0, s49, 0xe000
	s_nop 0
	global_load_lds_dwordx4 v[202:203], off
	s_waitcnt vmcnt(8)
	s_waitcnt lgkmcnt(0)
	s_barrier
; #define PG8_STAGE(bufoff, gbase, voff) do { _Pragma("unroll") for (int _i = 0; _i < 2; ++_i) \
;         __builtin_amdgcn_global_load_lds((const unsigned*)((const char*)(gbase) + (voff)[_i]), (PG8_LAS unsigned*)(lds + (bufoff) + ldsw + _i * 8192), 16, 0, 0); } while (0)
; #define PG8_LDA(dst, b, h) do { _Pragma("unroll") for (int m = 0; m < 4; ++m) _Pragma("unroll") for (int k = 0; k < 2; ++k) dst[m][k] = *(const PG8_LAS bf16x8*)(lds + PG8_SA(b, h) + aoff + m * 2048 + k * 1024); } while (0)
; #define PG8_LDB(dst, b, h) do { _Pragma("unroll") for (int n = 0; n < 2; ++n) _Pragma("unroll") for (int k = 0; k < 2; ++k) dst[n][k] = *(const PG8_LAS bf16x8*)(lds + PG8_SB(b, h) + boff + n * 2048 + k * 1024); } while (0)
; #define PG8_MMA(ai, bj, At, Bt) do { __builtin_amdgcn_s_setprio(1); _Pragma("unroll") for (int m = 0; m < 4; ++m) _Pragma("unroll") for (int n = 0; n < 2; ++n) _Pragma("unroll") for (int k = 0; k < 2; ++k) \
;         acc[ai][bj][m][n] = __builtin_amdgcn_mfma_f32_16x16x32_bf16(Bt[n][k], At[m][k], acc[ai][bj][m][n], 0, 0, 0); __builtin_amdgcn_s_setprio(0); } while (0)
; #define PG8_WAIT_V(n) asm volatile("s_waitcnt vmcnt(" #n ")" ::: "memory")
; #define PG8_WAIT_L(n) asm volatile("s_waitcnt lgkmcnt(" #n ")" ::: "memory")
; #define PG8_BAR __builtin_amdgcn_s_barrier()
; #define PG8_SCHED __builtin_amdgcn_sched_barrier(0)
; template <class Epi, class Sched, bool ALIGN_EPI = false, bool SP2 = false>
; __device__ __forceinline__ void gemm_phase(PG8_LAS unsigned char* lds, const Gemm g, const Sched& S, const Epi& E) {
;     ...
;             PG8_LDB(B0, 0, 0); PG8_LDB(B1, 0, 1); PG8_SCHED; PG8_LDA(At, 0, 0); PG8_STAGE(PG8_SA(1, 1), a1 + hstep, voffA);
;             PG8_WAIT_V(8); PG8_WAIT_L(0); PG8_BAR; PG8_MMA(0, 0, At, B0); PG8_MMA(0, 1, At, B1); PG8_BAR; PG8_SCHED;
;             PG8_LDA(At, 0, 1); PG8_STAGE(PG8_SB(0, 0), b2, voffB); PG8_STAGE(PG8_SB(0, 1), b2 + hstep, voffB); PG8_STAGE(PG8_SA(0, 0), a2, voffA);
;             PG8_WAIT_V(8); PG8_WAIT_L(0); PG8_BAR; PG8_MMA(1, 0, At, B0); PG8_MMA(1, 1, At, B1); PG8_BAR; PG8_SCHED;
	s_waitcnt lgkmcnt(0)
	v_mfma_f32_16x16x32_bf16 v[132:135], v[124:127], v[186:189], v[132:135]
	v_mfma_f32_16x16x32_bf16 v[128:131], v[140:143], v[186:189], v[128:131]
	v_mfma_f32_16x16x32_bf16 v[112:115], v[124:127], v[194:197], v[112:115]
	v_mfma_f32_16x16x32_bf16 v[108:111], v[140:143], v[194:197], v[108:111]
	v_mfma_f32_16x16x32_bf16 v[96:99], v[124:127], v[216:219], v[96:99]
	v_mfma_f32_16x16x32_bf16 v[92:95], v[140:143], v[216:219], v[92:95]
	v_mfma_f32_16x16x32_bf16 v[80:83], v[124:127], v[224:227], v[80:83]
	v_mfma_f32_16x16x32_bf16 v[76:79], v[140:143], v[224:227], v[76:79]
	v_mfma_f32_16x16x32_bf16 v[132:135], v[136:139], v[190:193], v[132:135]
	v_mfma_f32_16x16x32_bf16 v[128:131], v[144:147], v[190:193], v[128:131]
	v_mfma_f32_16x16x32_bf16 v[112:115], v[136:139], v[198:201], v[112:115]
	v_mfma_f32_16x16x32_bf16 v[108:111], v[144:147], v[198:201], v[108:111]
	v_mfma_f32_16x16x32_bf16 v[96:99], v[136:139], v[220:223], v[96:99]
	v_mfma_f32_16x16x32_bf16 v[92:95], v[144:147], v[220:223], v[92:95]
	v_mfma_f32_16x16x32_bf16 v[80:83], v[136:139], v[228:231], v[80:83]
	v_mfma_f32_16x16x32_bf16 v[76:79], v[144:147], v[228:231], v[76:79]
	v_mfma_f32_16x16x32_bf16 v[120:123], v[148:151], v[186:189], v[120:123]
	v_mfma_f32_16x16x32_bf16 v[116:119], v[156:159], v[186:189], v[116:119]
	v_mfma_f32_16x16x32_bf16 v[104:107], v[148:151], v[194:197], v[104:107]
	v_mfma_f32_16x16x32_bf16 v[100:103], v[156:159], v[194:197], v[100:103]
	v_mfma_f32_16x16x32_bf16 v[88:91], v[148:151], v[216:219], v[88:91]
	v_mfma_f32_16x16x32_bf16 v[84:87], v[156:159], v[216:219], v[84:87]
	v_mfma_f32_16x16x32_bf16 v[72:75], v[148:151], v[224:227], v[72:75]
	v_mfma_f32_16x16x32_bf16 v[68:71], v[156:159], v[224:227], v[68:71]
	v_mfma_f32_16x16x32_bf16 v[120:123], v[152:155], v[190:193], v[120:123]
	v_mfma_f32_16x16x32_bf16 v[116:119], v[182:185], v[190:193], v[116:119]
	v_mfma_f32_16x16x32_bf16 v[104:107], v[152:155], v[198:201], v[104:107]
	v_mfma_f32_16x16x32_bf16 v[100:103], v[182:185], v[198:201], v[100:103]
	v_mfma_f32_16x16x32_bf16 v[88:91], v[152:155], v[220:223], v[88:91]
	v_mfma_f32_16x16x32_bf16 v[84:87], v[182:185], v[220:223], v[84:87]
	v_mfma_f32_16x16x32_bf16 v[72:75], v[152:155], v[228:231], v[72:75]
	v_mfma_f32_16x16x32_bf16 v[68:71], v[182:185], v[228:231], v[68:71]
	s_barrier
	s_add_i32 s68, s70, s48
	s_add_u32 s98, s38, 0x80
	s_addc_u32 s99, s39, 0
	s_mov_b32 m0, s68
	ds_read_b128 v[186:189], v214 offset:16384
	ds_read_b128 v[190:193], v214 offset:17408
	ds_read_b128 v[194:197], v214 offset:18432
	ds_read_b128 v[198:201], v214 offset:19456
	ds_read_b128 v[216:219], v214 offset:20480
	ds_read_b128 v[220:223], v214 offset:21504
	ds_read_b128 v[224:227], v214 offset:22528
	ds_read_b128 v[228:231], v214 offset:23552
	global_load_lds_dwordx4 v174, s[38:39]
	s_add_i32 m0, s68, 0x2000
	s_add_u32 s68, s38, 0x160000
	s_addc_u32 s69, s39, 0
	s_add_i32 s70, s71, s48
	global_load_lds_dwordx4 v0, s[38:39]
	s_mov_b32 m0, s70
	s_add_u32 s100, s46, 0x80
	s_addc_u32 s101, s47, 0
	s_nop 0
	global_load_lds_dwordx4 v174, s[68:69]
	s_add_i32 m0, s70, 0x2000
	s_nop 0
	global_load_lds_dwordx4 v0, s[68:69]
	s_mov_b32 m0, s49
	s_nop 0
	global_load_lds_dwordx4 v176, s[46:47]
	s_mov_b32 m0, s50
	s_nop 0
	global_load_lds_dwordx4 v172, s[46:47]
	s_waitcnt vmcnt(8)
	s_waitcnt lgkmcnt(0)
	s_barrier
	s_waitcnt lgkmcnt(0)
	v_mfma_f32_16x16x32_bf16 v[64:67], v[124:127], v[186:189], v[64:67]
	v_mfma_f32_16x16x32_bf16 v[60:63], v[140:143], v[186:189], v[60:63]
	v_mfma_f32_16x16x32_bf16 v[48:51], v[124:127], v[194:197], v[48:51]
	v_mfma_f32_16x16x32_bf16 v[44:47], v[140:143], v[194:197], v[44:47]
	v_mfma_f32_16x16x32_bf16 v[32:35], v[124:127], v[216:219], v[32:35]
	v_mfma_f32_16x16x32_bf16 v[28:31], v[140:143], v[216:219], v[28:31]
	v_mfma_f32_16x16x32_bf16 v[16:19], v[124:127], v[224:227], v[16:19]
	v_mfma_f32_16x16x32_bf16 v[12:15], v[140:143], v[224:227], v[12:15]
	v_mfma_f32_16x16x32_bf16 v[64:67], v[136:139], v[190:193], v[64:67]
	v_mfma_f32_16x16x32_bf16 v[60:63], v[144:147], v[190:193], v[60:63]
	v_mfma_f32_16x16x32_bf16 v[48:51], v[136:139], v[198:201], v[48:51]
	v_mfma_f32_16x16x32_bf16 v[44:47], v[144:147], v[198:201], v[44:47]
	v_mfma_f32_16x16x32_bf16 v[32:35], v[136:139], v[220:223], v[32:35]
	v_mfma_f32_16x16x32_bf16 v[28:31], v[144:147], v[220:223], v[28:31]
	v_mfma_f32_16x16x32_bf16 v[16:19], v[136:139], v[228:231], v[16:19]
	v_mfma_f32_16x16x32_bf16 v[12:15], v[144:147], v[228:231], v[12:15]
	v_mfma_f32_16x16x32_bf16 v[56:59], v[148:151], v[186:189], v[56:59]
	v_mfma_f32_16x16x32_bf16 v[52:55], v[156:159], v[186:189], v[52:55]
	v_mfma_f32_16x16x32_bf16 v[40:43], v[148:151], v[194:197], v[40:43]
	v_mfma_f32_16x16x32_bf16 v[36:39], v[156:159], v[194:197], v[36:39]
	v_mfma_f32_16x16x32_bf16 v[24:27], v[148:151], v[216:219], v[24:27]
	v_mfma_f32_16x16x32_bf16 v[20:23], v[156:159], v[216:219], v[20:23]
	v_mfma_f32_16x16x32_bf16 v[8:11], v[148:151], v[224:227], v[8:11]
	v_mfma_f32_16x16x32_bf16 v[4:7], v[156:159], v[224:227], v[4:7]
	v_mfma_f32_16x16x32_bf16 v[56:59], v[152:155], v[190:193], v[56:59]
	v_mfma_f32_16x16x32_bf16 v[52:55], v[182:185], v[190:193], v[52:55]
	v_mfma_f32_16x16x32_bf16 v[40:43], v[152:155], v[198:201], v[40:43]
	v_mfma_f32_16x16x32_bf16 v[36:39], v[182:185], v[198:201], v[36:39]
	v_mfma_f32_16x16x32_bf16 v[24:27], v[152:155], v[220:223], v[24:27]
	v_mfma_f32_16x16x32_bf16 v[20:23], v[182:185], v[220:223], v[20:23]
	v_mfma_f32_16x16x32_bf16 v[8:11], v[152:155], v[228:231], v[8:11]
	v_mfma_f32_16x16x32_bf16 v[4:7], v[182:185], v[228:231], v[4:7]
	s_barrier
; #define PG8_STAGE(bufoff, gbase, voff) do { _Pragma("unroll") for (int _i = 0; _i < 2; ++_i) \
;         __builtin_amdgcn_global_load_lds((const unsigned*)((const char*)(gbase) + (voff)[_i]), (PG8_LAS unsigned*)(lds + (bufoff) + ldsw + _i * 8192), 16, 0, 0); } while (0)
; #define PG8_LDA(dst, b, h) do { _Pragma("unroll") for (int m = 0; m < 4; ++m) _Pragma("unroll") for (int k = 0; k < 2; ++k) dst[m][k] = *(const PG8_LAS bf16x8*)(lds + PG8_SA(b, h) + aoff + m * 2048 + k * 1024); } while (0)
; #define PG8_LDB(dst, b, h) do { _Pragma("unroll") for (int n = 0; n < 2; ++n) _Pragma("unroll") for (int k = 0; k < 2; ++k) dst[n][k] = *(const PG8_LAS bf16x8*)(lds + PG8_SB(b, h) + boff + n * 2048 + k * 1024); } while (0)
; #define PG8_MMA(ai, bj, At, Bt) do { __builtin_amdgcn_s_setprio(1); _Pragma("unroll") for (int m = 0; m < 4; ++m) _Pragma("unroll") for (int n = 0; n < 2; ++n) _Pragma("unroll") for (int k = 0; k < 2; ++k) \
;         acc[ai][bj][m][n] = __builtin_amdgcn_mfma_f32_16x16x32_bf16(Bt[n][k], At[m][k], acc[ai][bj][m][n], 0, 0, 0); __builtin_amdgcn_s_setprio(0); } while (0)
; #define PG8_WAIT_V(n) asm volatile("s_waitcnt vmcnt(" #n ")" ::: "memory")
; #define PG8_WAIT_L(n) asm volatile("s_waitcnt lgkmcnt(" #n ")" ::: "memory")
; #define PG8_BAR __builtin_amdgcn_s_barrier()
; #define PG8_SCHED __builtin_amdgcn_sched_barrier(0)
; template <class Epi, class Sched, bool ALIGN_EPI = false, bool SP2 = false>
; __device__ __forceinline__ void gemm_phase(PG8_LAS unsigned char* lds, const Gemm g, const Sched& S, const Epi& E) {
;     ...
;             PG8_LDB(B0, 1, 0); PG8_LDB(B1, 1, 1); PG8_SCHED; PG8_LDA(At, 1, 0); PG8_STAGE(PG8_SA(0, 1), a2 + hstep, voffA);
;             PG8_WAIT_V(8); PG8_WAIT_L(0); PG8_BAR; PG8_MMA(0, 0, At, B0); PG8_MMA(0, 1, At, B1); PG8_BAR; PG8_SCHED;
;             PG8_LDA(At, 1, 1); PG8_STAGE(PG8_SB(1, 0), b3, voffB); PG8_STAGE(PG8_SB(1, 1), b3 + hstep, voffB); PG8_STAGE(PG8_SA(1, 0), a3, voffA);
;             PG8_WAIT_V(8); PG8_WAIT_L(0); PG8_BAR; PG8_MMA(1, 0, At, B0); PG8_MMA(1, 1, At, B1); PG8_BAR; PG8_SCHED;
;     ...
;         if constexpr (ALIGN_EPI) { if (wr == 0) PG8_BAR; }
	s_add_i32 s68, 0, 0x18000
	s_add_i32 s69, 0, 0x1c000
	ds_read_b128 v[124:127], v170
	ds_read_b128 v[136:139], v170 offset:1024
	ds_read_b128 v[140:143], v170 offset:2048
	ds_read_b128 v[144:147], v170 offset:3072
	ds_read_b128 v[148:151], v171
	ds_read_b128 v[152:155], v171 offset:1024
	ds_read_b128 v[156:159], v171 offset:2048
	ds_read_b128 v[182:185], v171 offset:3072
	s_add_u32 s46, s46, 0x160000
	s_addc_u32 s47, s47, 0
	s_mov_b32 m0, s51
	ds_read_b128 v[186:189], v214 offset:32768
	ds_read_b128 v[190:193], v214 offset:33792
	ds_read_b128 v[194:197], v214 offset:34816
	ds_read_b128 v[198:201], v214 offset:35840
	ds_read_b128 v[216:219], v214 offset:36864
	ds_read_b128 v[220:223], v214 offset:37888
	ds_read_b128 v[224:227], v214 offset:38912
	ds_read_b128 v[228:231], v214 offset:39936
	global_load_lds_dwordx4 v176, s[46:47]
	s_mov_b32 m0, s52
	s_nop 0
	global_load_lds_dwordx4 v172, s[46:47]
	s_waitcnt vmcnt(8)
	s_waitcnt lgkmcnt(0)
	s_barrier
	s_waitcnt lgkmcnt(0)
	v_mfma_f32_16x16x32_bf16 v[132:135], v[124:127], v[186:189], v[132:135]
	v_mfma_f32_16x16x32_bf16 v[128:131], v[140:143], v[186:189], v[128:131]
	v_mfma_f32_16x16x32_bf16 v[112:115], v[124:127], v[194:197], v[112:115]
	v_mfma_f32_16x16x32_bf16 v[108:111], v[140:143], v[194:197], v[108:111]
	v_mfma_f32_16x16x32_bf16 v[96:99], v[124:127], v[216:219], v[96:99]
	v_mfma_f32_16x16x32_bf16 v[92:95], v[140:143], v[216:219], v[92:95]
	v_mfma_f32_16x16x32_bf16 v[80:83], v[124:127], v[224:227], v[80:83]
	v_mfma_f32_16x16x32_bf16 v[76:79], v[140:143], v[224:227], v[76:79]
	v_mfma_f32_16x16x32_bf16 v[132:135], v[136:139], v[190:193], v[132:135]
	v_mfma_f32_16x16x32_bf16 v[128:131], v[144:147], v[190:193], v[128:131]
	v_mfma_f32_16x16x32_bf16 v[112:115], v[136:139], v[198:201], v[112:115]
	v_mfma_f32_16x16x32_bf16 v[108:111], v[144:147], v[198:201], v[108:111]
	v_mfma_f32_16x16x32_bf16 v[96:99], v[136:139], v[220:223], v[96:99]
	v_mfma_f32_16x16x32_bf16 v[92:95], v[144:147], v[220:223], v[92:95]
	v_mfma_f32_16x16x32_bf16 v[80:83], v[136:139], v[228:231], v[80:83]
	v_mfma_f32_16x16x32_bf16 v[76:79], v[144:147], v[228:231], v[76:79]
	v_mfma_f32_16x16x32_bf16 v[120:123], v[148:151], v[186:189], v[120:123]
	v_mfma_f32_16x16x32_bf16 v[116:119], v[156:159], v[186:189], v[116:119]
	v_mfma_f32_16x16x32_bf16 v[104:107], v[148:151], v[194:197], v[104:107]
	v_mfma_f32_16x16x32_bf16 v[100:103], v[156:159], v[194:197], v[100:103]
	v_mfma_f32_16x16x32_bf16 v[88:91], v[148:151], v[216:219], v[88:91]
	v_mfma_f32_16x16x32_bf16 v[84:87], v[156:159], v[216:219], v[84:87]
	v_mfma_f32_16x16x32_bf16 v[72:75], v[148:151], v[224:227], v[72:75]
	v_mfma_f32_16x16x32_bf16 v[68:71], v[156:159], v[224:227], v[68:71]
	v_mfma_f32_16x16x32_bf16 v[120:123], v[152:155], v[190:193], v[120:123]
	v_mfma_f32_16x16x32_bf16 v[116:119], v[182:185], v[190:193], v[116:119]
	v_mfma_f32_16x16x32_bf16 v[104:107], v[152:155], v[198:201], v[104:107]
	v_mfma_f32_16x16x32_bf16 v[100:103], v[182:185], v[198:201], v[100:103]
	v_mfma_f32_16x16x32_bf16 v[88:91], v[152:155], v[220:223], v[88:91]
	v_mfma_f32_16x16x32_bf16 v[84:87], v[182:185], v[220:223], v[84:87]
	v_mfma_f32_16x16x32_bf16 v[72:75], v[152:155], v[228:231], v[72:75]
	v_mfma_f32_16x16x32_bf16 v[68:71], v[182:185], v[228:231], v[68:71]
	s_barrier
	s_add_i32 s46, s68, s48
	s_mov_b32 m0, s46
	ds_read_b128 v[186:189], v214 offset:49152
	ds_read_b128 v[190:193], v214 offset:50176
	ds_read_b128 v[194:197], v214 offset:51200
	ds_read_b128 v[198:201], v214 offset:52224
	ds_read_b128 v[216:219], v214 offset:53248
	ds_read_b128 v[220:223], v214 offset:54272
	ds_read_b128 v[224:227], v214 offset:55296
	ds_read_b128 v[228:231], v214 offset:56320
	global_load_lds_dwordx4 v174, s[98:99]
	s_add_i32 m0, s46, 0x2000
	s_add_u32 s38, s38, 0x160080
	s_addc_u32 s39, s39, 0
	s_add_i32 s46, s69, s48
	global_load_lds_dwordx4 v0, s[98:99]
	s_mov_b32 m0, s46
	s_nop 0
	global_load_lds_dwordx4 v174, s[38:39]
	s_add_i32 m0, s46, 0x2000
	s_nop 0
	global_load_lds_dwordx4 v0, s[38:39]
	s_mov_b32 m0, s53
	s_nop 0
	global_load_lds_dwordx4 v176, s[100:101]
	s_mov_b32 m0, s57
	s_nop 0
	global_load_lds_dwordx4 v172, s[100:101]
	s_waitcnt vmcnt(8)
	s_waitcnt lgkmcnt(0)
	s_barrier
	s_waitcnt lgkmcnt(0)
	v_mfma_f32_16x16x32_bf16 v[64:67], v[124:127], v[186:189], v[64:67]
	v_mfma_f32_16x16x32_bf16 v[60:63], v[140:143], v[186:189], v[60:63]
	v_mfma_f32_16x16x32_bf16 v[48:51], v[124:127], v[194:197], v[48:51]
	v_mfma_f32_16x16x32_bf16 v[44:47], v[140:143], v[194:197], v[44:47]
	v_mfma_f32_16x16x32_bf16 v[32:35], v[124:127], v[216:219], v[32:35]
	v_mfma_f32_16x16x32_bf16 v[28:31], v[140:143], v[216:219], v[28:31]
	v_mfma_f32_16x16x32_bf16 v[16:19], v[124:127], v[224:227], v[16:19]
	v_mfma_f32_16x16x32_bf16 v[12:15], v[140:143], v[224:227], v[12:15]
	v_mfma_f32_16x16x32_bf16 v[64:67], v[136:139], v[190:193], v[64:67]
	v_mfma_f32_16x16x32_bf16 v[60:63], v[144:147], v[190:193], v[60:63]
	v_mfma_f32_16x16x32_bf16 v[48:51], v[136:139], v[198:201], v[48:51]
	v_mfma_f32_16x16x32_bf16 v[44:47], v[144:147], v[198:201], v[44:47]
	v_mfma_f32_16x16x32_bf16 v[32:35], v[136:139], v[220:223], v[32:35]
	v_mfma_f32_16x16x32_bf16 v[28:31], v[144:147], v[220:223], v[28:31]
	v_mfma_f32_16x16x32_bf16 v[16:19], v[136:139], v[228:231], v[16:19]
	v_mfma_f32_16x16x32_bf16 v[12:15], v[144:147], v[228:231], v[12:15]
	v_mfma_f32_16x16x32_bf16 v[56:59], v[148:151], v[186:189], v[56:59]
	v_mfma_f32_16x16x32_bf16 v[52:55], v[156:159], v[186:189], v[52:55]
	v_mfma_f32_16x16x32_bf16 v[40:43], v[148:151], v[194:197], v[40:43]
	v_mfma_f32_16x16x32_bf16 v[36:39], v[156:159], v[194:197], v[36:39]
	v_mfma_f32_16x16x32_bf16 v[24:27], v[148:151], v[216:219], v[24:27]
	v_mfma_f32_16x16x32_bf16 v[20:23], v[156:159], v[216:219], v[20:23]
	v_mfma_f32_16x16x32_bf16 v[8:11], v[148:151], v[224:227], v[8:11]
	v_mfma_f32_16x16x32_bf16 v[4:7], v[156:159], v[224:227], v[4:7]
	v_mfma_f32_16x16x32_bf16 v[56:59], v[152:155], v[190:193], v[56:59]
	v_mfma_f32_16x16x32_bf16 v[52:55], v[182:185], v[190:193], v[52:55]
	v_mfma_f32_16x16x32_bf16 v[40:43], v[152:155], v[198:201], v[40:43]
	v_mfma_f32_16x16x32_bf16 v[36:39], v[182:185], v[198:201], v[36:39]
	v_mfma_f32_16x16x32_bf16 v[24:27], v[152:155], v[220:223], v[24:27]
	v_mfma_f32_16x16x32_bf16 v[20:23], v[182:185], v[220:223], v[20:23]
	v_mfma_f32_16x16x32_bf16 v[8:11], v[152:155], v[228:231], v[8:11]
	v_mfma_f32_16x16x32_bf16 v[4:7], v[182:185], v[228:231], v[4:7]
	s_barrier
	s_add_i32 s67, s67, 2
	s_add_u32 s2, s2, 0x100
	s_addc_u32 s3, s3, 0
	s_cmpk_gt_u32 s67, 0x55
	s_cbranch_scc0 .LBB0_1278
	s_and_b64 vcc, exec, s[12:13]
	s_cbranch_vccz .LBB0_1281
	s_barrier
; __device__ __forceinline__ float ss_get(const ss_t* p) { const ss_t v = *p; return (float)(unsigned)(v >> 32) + (float)(unsigned)v * 2.3283064365386963e-10f; }
;     __device__ __forceinline__ void operator()(const f32x4 (&acc)[2][2][4][2], const Unit& u, int wr, int wc, int fr, int fq) const {
;         int row0 = u.pm * BM + wr * 64 + fr; asm volatile("" : "+v"(row0));     const int col0 = u.pn * BM + wc * 32 + 8 * fq;
; #pragma unroll
;         for (int ai = 0; ai < 2; ++ai) {
;             u32x4 res[4][2];
; #pragma unroll
;             for (int m = 0; m < 4; ++m) { const bf16_t* rowp = XB + (size_t)(row0 + ai * HALF + m * 16) * ldc + col0;
; #pragma unroll
;                 for (int bj = 0; bj < 2; ++bj) res[m][bj] = *(const u32x4*)(rowp + bj * HALF); }
;             asm volatile("" ::: "memory");
; #pragma unroll
;             for (int m = 0; m < 4; ++m) { const int row = row0 + ai * HALF + m * 16; const size_t off = (size_t)row * ldc + col0;
;                 float rs = 1.0f; if (KS) rs = 1.0f / sqrtf(ss_get(ssb + row) * (1.0f / 1024.f) + 1e-6f);
;                 float sq = 0.f;
; #pragma unroll
;                 for (int bj = 0; bj < 2; ++bj) { const u32x4 r = res[m][bj];
;                     const f32x4 x0 = (f32x4){__uint_as_float(r.x << 16), __uint_as_float(r.x & 0xffff0000u), __uint_as_float(r.y << 16), __uint_as_float(r.y & 0xffff0000u)};
;                     const f32x4 x1 = (f32x4){__uint_as_float(r.z << 16), __uint_as_float(r.z & 0xffff0000u), __uint_as_float(r.w << 16), __uint_as_float(r.w & 0xffff0000u)};
;                     const f32x4 v0 = x0 + acc[ai][bj][m][0] * rs, v1 = x1 + acc[ai][bj][m][1] * rs;
;                     if (OUT) { *(f32x4*)(OUT + off + bj * HALF) = v0; *(f32x4*)(OUT + off + bj * HALF + 4) = v1; }
.LBB0_1281:
	s_setprio 0
	v_mov_b32_e32 v182, v212
	v_lshl_or_b32 v184, s60, 8, v213
	v_ashrrev_i32_e32 v185, 31, v184
	v_ashrrev_i32_e32 v183, 31, v182
	v_add_u32_e32 v198, 16, v182
	v_lshl_add_u64 v[186:187], v[184:185], 1, s[64:65]
	v_lshlrev_b64 v[124:125], 12, v[182:183]
	v_ashrrev_i32_e32 v199, 31, v198
	v_add_u32_e32 v194, 32, v182
	v_lshl_add_u64 v[200:201], v[186:187], 0, v[124:125]
	v_lshlrev_b64 v[124:125], 12, v[198:199]
	v_ashrrev_i32_e32 v195, 31, v194
	v_add_u32_e32 v190, 48, v182
	v_lshl_add_u64 v[196:197], v[186:187], 0, v[124:125]
	v_lshlrev_b64 v[124:125], 12, v[194:195]
	v_ashrrev_i32_e32 v191, 31, v190
	v_lshl_add_u64 v[192:193], v[186:187], 0, v[124:125]
	v_lshlrev_b64 v[124:125], 12, v[190:191]
	global_load_dwordx4 v[216:219], v[200:201], off
	global_load_dwordx4 v[156:159], v[200:201], off offset:256
	v_lshl_add_u64 v[188:189], v[186:187], 0, v[124:125]
	global_load_dwordx4 v[152:155], v[196:197], off
	global_load_dwordx4 v[148:151], v[196:197], off offset:256
	global_load_dwordx4 v[144:147], v[192:193], off
	global_load_dwordx4 v[140:143], v[192:193], off offset:256
	global_load_dwordx4 v[136:139], v[188:189], off
	global_load_dwordx4 v[124:127], v[188:189], off offset:256
	v_cndmask_b32_e64 v202, 0, 1, s[40:41]
	v_cmp_ne_u32_e64 s[38:39], 1, v202
	v_lshlrev_b64 v[202:203], 11, v[182:183]
	v_lshl_add_u64 v[202:203], v[202:203], 0, v[184:185]
	s_mov_b64 s[2:3], -1
	s_andn2_b64 vcc, exec, s[40:41]
	v_lshl_add_u64 v[202:203], v[202:203], 2, s[6:7]
	s_waitcnt vmcnt(0)
	v_lshlrev_b32_e32 v220, 16, v216
	v_and_b32_e32 v221, 0xffff0000, v216
	v_lshlrev_b32_e32 v216, 16, v217
	v_and_b32_e32 v217, 0xffff0000, v217
	v_lshlrev_b32_e32 v222, 16, v218
	v_and_b32_e32 v223, 0xffff0000, v218
	v_lshlrev_b32_e32 v218, 16, v219
	v_and_b32_e32 v219, 0xffff0000, v219
	v_pk_add_f32 v[134:135], v[134:135], v[216:217]
	v_pk_add_f32 v[132:133], v[132:133], v[220:221]
	v_pk_add_f32 v[130:131], v[130:131], v[218:219]
	v_pk_add_f32 v[128:129], v[128:129], v[222:223]
	s_cbranch_vccnz .LBB0_1283
	s_mov_b64 s[2:3], 0
	global_store_dwordx4 v[202:203], v[132:135], off
	global_store_dwordx4 v[202:203], v[128:131], off offset:16
